# FoX: hand-written pipelined tile block for tiles below the wave diagonal; hgrn_scan inner loop unrolled with loads two groups ahead
# speedup vs baseline: 1.0286x; 1.0093x over previous
.LBB0_63:
	v_cmp_ge_i32_e32 vcc, s23, v171
	v_cmp_le_i32_e64 s[4:5], s23, v170
	s_and_b64 s[4:5], vcc, s[4:5]
	s_and_saveexec_b64 s[16:17], s[4:5]
	s_cbranch_execz .LBB0_65
	v_readfirstlane_b32 s4, v170
	s_cmp_lt_i32 s23, s4
	s_cbranch_scc1 .Lfoxf_fast
	v_mov_b32_e32 v64, v157
	v_mov_b32_e32 v65, v156
	v_mov_b32_e32 v66, v151
	v_mov_b32_e32 v67, v150
	s_nop 1
	v_permlane16_swap_b32_e32 v157, v64
	v_permlane16_swap_b32_e32 v156, v65
	v_permlane16_swap_b32_e32 v151, v66
	v_permlane16_swap_b32_e32 v150, v67
	v_add_f32_e32 v157, v157, v64
	v_add_f32_e32 v156, v156, v65
	v_add_f32_e32 v151, v151, v66
	v_add_f32_e32 v150, v150, v67
	v_mov_b32_e32 v64, v157
	v_mov_b32_e32 v65, v156
	v_mov_b32_e32 v66, v151
	v_mov_b32_e32 v67, v150
	s_nop 1
	v_permlane32_swap_b32_e32 v157, v64
	v_permlane32_swap_b32_e32 v156, v65
	v_permlane32_swap_b32_e32 v151, v66
	v_permlane32_swap_b32_e32 v150, v67
	v_add_f32_e32 v157, v157, v64
	v_add_f32_e32 v156, v156, v65
	v_add_f32_e32 v151, v151, v66
	v_add_f32_e32 v150, v150, v67
	s_lshl_b32 s84, s23, 6
	v_lshl_add_u64 v[158:159], s[84:85], 2, v[146:147]
	global_load_dwordx4 v[88:91], v[158:159], off
	global_load_dwordx4 v[84:87], v[158:159], off offset:64
	s_lshl_b32 s4, s21, 14
	v_or_b32_e32 v109, s4, v178
	v_and_b32_e32 v64, 64, v200
	v_add_u32_e32 v108, v175, v176
	v_add_u32_e32 v196, v109, v176
	v_add_u32_e32 v162, v175, v177
	v_add_u32_e32 v82, 64, v64
	ds_read_b128 v[64:67], v108 offset:32768
	ds_read_b128 v[72:75], v108 offset:34816
	ds_read_b128 v[76:79], v162 offset:32768
	ds_read_b128 v[68:71], v162 offset:34816
	ds_read_b128 v[112:115], v196
	ds_read_b128 v[116:119], v196 offset:2048
	v_add_u32_e32 v194, v109, v177
	ds_read_b128 v[120:123], v194
	ds_read_b128 v[124:127], v194 offset:2048
	v_xor_b32_e32 v80, 16, v200
	v_xor_b32_e32 v81, 32, v200
	v_cmp_lt_i32_e32 vcc, v80, v82
	s_waitcnt lgkmcnt(0)
	v_mfma_f32_16x16x32_bf16 v[92:95], v[116:119], v[64:67], 0
	v_cndmask_b32_e32 v96, v200, v80, vcc
	v_cmp_lt_i32_e32 vcc, v81, v82
	v_lshlrev_b32_e32 v187, 2, v96
	v_mfma_f32_16x16x32_bf16 v[92:95], v[124:127], v[76:79], v[92:95]
	v_cndmask_b32_e32 v100, v200, v81, vcc
	v_or_b32_e32 v191, s84, v180
	v_or_b32_e32 v110, s4, v179
	v_mfma_f32_16x16x32_bf16 v[80:83], v[112:115], v[64:67], 0
	v_or_b32_e32 v219, 2, v191
	v_cmp_lt_i32_e64 s[4:5], v191, v130
	v_or_b32_e32 v216, 3, v191
	v_mfma_f32_16x16x32_bf16 v[96:99], v[120:123], v[76:79], v[80:83]
	v_or_b32_e32 v218, 16, v191
	v_lshlrev_b32_e32 v149, 2, v100
	v_or_b32_e32 v215, 17, v191
	v_cmp_gt_i32_e32 vcc, v191, v130
	v_or_b32_e32 v217, 18, v191
	v_or_b32_e32 v214, 19, v191
	v_add_u32_e32 v101, v109, v181
	v_add_u32_e32 v102, v109, v182
	s_waitcnt vmcnt(0)
	ds_read2st64_b64 v[208:211], v101 offset0:16 offset1:20
	ds_read2st64_b64 v[80:83], v102 offset0:16 offset1:20
	v_add_u32_e32 v105, v110, v182
	v_add_u32_e32 v104, v110, v181
	v_or_b32_e32 v192, 32, v191
	v_or_b32_e32 v190, 33, v191
	v_or_b32_e32 v193, 48, v191
	v_or_b32_e32 v197, 50, v191
	v_sub_f32_e32 v103, v131, v89
	v_sub_f32_e32 v106, v131, v90
	v_sub_f32_e32 v160, v131, v85
	v_add_f32_e32 v97, v103, v97
	v_sub_f32_e32 v107, v131, v91
	v_sub_f32_e32 v161, v131, v86
	v_add_f32_e32 v98, v106, v98
	v_add_f32_e32 v93, v160, v93
	v_cndmask_b32_e64 v160, v204, v97, s[4:5]
	v_cmp_le_i32_e64 s[4:5], v219, v130
	v_sub_f32_e32 v100, v131, v88
	v_sub_f32_e32 v111, v131, v84
	v_sub_f32_e32 v163, v131, v87
	v_add_f32_e32 v99, v107, v99
	v_add_f32_e32 v94, v161, v94
	v_cndmask_b32_e64 v161, v204, v98, s[4:5]
	v_cmp_le_i32_e64 s[4:5], v216, v130
	v_add_f32_e32 v96, v100, v96
	v_add_f32_e32 v92, v111, v92
	v_add_f32_e32 v95, v163, v95
	v_cndmask_b32_e64 v163, v204, v99, s[4:5]
	v_cmp_le_i32_e64 s[4:5], v218, v130
	v_cndmask_b32_e32 v111, v96, v204, vcc
	v_max3_f32 v96, v111, s75, v160
	v_cndmask_b32_e64 v92, v204, v92, s[4:5]
	v_cmp_le_i32_e64 s[4:5], v215, v130
	v_max3_f32 v96, v96, v161, v163
	v_sub_f32_e32 v234, v168, v88
	v_cndmask_b32_e64 v93, v204, v93, s[4:5]
	v_cmp_le_i32_e64 s[4:5], v217, v130
	v_max3_f32 v96, v96, v92, v93
	v_sub_f32_e32 v235, v168, v89
	v_cndmask_b32_e64 v94, v204, v94, s[4:5]
	v_cmp_le_i32_e64 s[4:5], v214, v130
	v_sub_f32_e32 v236, v168, v90
	v_sub_f32_e32 v237, v168, v91
	v_cndmask_b32_e64 v95, v204, v95, s[4:5]
	v_max3_f32 v106, v96, v94, v95
	ds_bpermute_b32 v107, v187, v106
	ds_read_b64 v[100:101], v101 offset:12288
	ds_read_b64 v[102:103], v102 offset:12288
	ds_read_b64 v[96:97], v104 offset:8192
	ds_read_b64 v[98:99], v105 offset:8192
	s_waitcnt lgkmcnt(6)
	v_mov_b32_e32 v105, v209
	v_sub_f32_e32 v242, v169, v88
	v_sub_f32_e32 v243, v169, v89
	s_waitcnt lgkmcnt(4)
	v_max_f32_e32 v107, v107, v107
	v_max_f32_e32 v164, v106, v107
	ds_bpermute_b32 v165, v149, v164
	v_mov_b32_e32 v106, v80
	v_mov_b32_e32 v107, v81
	v_mov_b32_e32 v80, v210
	v_mov_b32_e32 v81, v211
	s_waitcnt lgkmcnt(0)
	v_max3_f32 v209, v186, v164, v165
	v_sub_f32_e32 v92, v92, v209
	v_exp_f32_e32 v229, v92
	v_sub_f32_e32 v92, v93, v209
	v_mfma_f32_16x16x32_bf16 v[210:213], v[112:115], v[72:75], 0
	v_sub_f32_e32 v160, v160, v209
	v_exp_f32_e32 v231, v92
	v_sub_f32_e32 v92, v94, v209
	v_sub_f32_e32 v161, v161, v209
	v_exp_f32_e32 v165, v160
	v_sub_f32_e32 v160, v163, v209
	v_exp_f32_e32 v93, v92
	v_sub_f32_e32 v92, v95, v209
	v_exp_f32_e32 v225, v161
	v_exp_f32_e32 v227, v160
	v_exp_f32_e32 v95, v92
	v_sub_f32_e32 v92, v155, v88
	v_sub_f32_e32 v94, v155, v89
	v_sub_f32_e32 v160, v155, v90
	v_sub_f32_e32 v161, v155, v91
	v_sub_f32_e32 v244, v169, v90
	v_sub_f32_e32 v245, v169, v91
	v_mfma_f32_16x16x32_bf16 v[88:91], v[116:119], v[72:75], 0
	v_sub_f32_e32 v164, v186, v209
	v_mov_b32_e32 v104, v208
	v_exp_f32_e32 v208, v164
	v_mfma_f32_16x16x32_bf16 v[220:223], v[120:123], v[68:71], v[210:213]
	v_sub_f32_e32 v163, v155, v84
	v_sub_f32_e32 v164, v155, v85
	v_sub_f32_e32 v188, v155, v86
	v_sub_f32_e32 v189, v155, v87
	v_sub_f32_e32 v238, v168, v84
	v_sub_f32_e32 v239, v168, v85
	v_sub_f32_e32 v240, v168, v86
	v_sub_f32_e32 v241, v168, v87
	v_sub_f32_e32 v246, v169, v84
	v_sub_f32_e32 v247, v169, v85
	v_sub_f32_e32 v248, v169, v86
	v_sub_f32_e32 v249, v169, v87
	v_mfma_f32_16x16x32_bf16 v[84:87], v[124:127], v[68:71], v[88:91]
	v_cmp_le_i32_e64 s[4:5], v191, v172
	v_add_u32_e32 v186, v109, v183
	v_add_u32_e32 v210, v109, v184
	v_add_f32_e32 v88, v92, v220
	v_cndmask_b32_e64 v88, v204, v88, s[4:5]
	v_add_f32_e32 v89, v94, v221
	v_cmp_lt_i32_e64 s[4:5], v191, v172
	v_add_f32_e32 v91, v160, v222
	v_add_f32_e32 v92, v161, v223
	v_cndmask_b32_e64 v90, v204, v89, s[4:5]
	v_cmp_le_i32_e64 s[4:5], v219, v172
	v_add_f32_e32 v84, v163, v84
	v_cndmask_b32_e32 v94, v84, v204, vcc
	v_cndmask_b32_e64 v91, v204, v91, s[4:5]
	v_cmp_le_i32_e64 s[4:5], v216, v172
	v_add_f32_e32 v84, v164, v85
	v_max3_f32 v89, v88, s75, v90
	v_cndmask_b32_e64 v92, v204, v92, s[4:5]
	v_cmp_le_i32_e64 s[4:5], v215, v172
	v_add_f32_e32 v85, v188, v86
	v_max3_f32 v89, v89, v91, v92
	v_cndmask_b32_e64 v109, v204, v84, s[4:5]
	v_cmp_le_i32_e64 s[4:5], v217, v172
	v_max3_f32 v84, v89, v94, v109
	v_sub_f32_e32 v111, v111, v209
	v_cndmask_b32_e64 v160, v204, v85, s[4:5]
	v_add_f32_e32 v85, v189, v87
	v_cmp_le_i32_e64 s[4:5], v214, v172
	v_exp_f32_e32 v111, v111
	v_add_u32_e32 v212, v110, v183
	v_cndmask_b32_e64 v161, v204, v85, s[4:5]
	v_max3_f32 v84, v84, v160, v161
	ds_bpermute_b32 v85, v187, v84
	v_add_u32_e32 v213, v110, v184
	v_pk_mul_f32 v[62:63], v[62:63], v[208:209] op_sel_hi:[1,0]
	v_pk_mul_f32 v[60:61], v[60:61], v[208:209] op_sel_hi:[1,0]
	v_pk_mul_f32 v[58:59], v[58:59], v[208:209] op_sel_hi:[1,0]
	s_waitcnt lgkmcnt(0)
	v_max_f32_e32 v85, v85, v85
	v_max_f32_e32 v85, v84, v85
	ds_bpermute_b32 v86, v149, v85
	v_pk_mul_f32 v[56:57], v[56:57], v[208:209] op_sel_hi:[1,0]
	v_pk_mul_f32 v[54:55], v[54:55], v[208:209] op_sel_hi:[1,0]
	v_pk_mul_f32 v[52:53], v[52:53], v[208:209] op_sel_hi:[1,0]
	v_pk_mul_f32 v[50:51], v[50:51], v[208:209] op_sel_hi:[1,0]
	s_waitcnt lgkmcnt(0)
	v_max3_f32 v195, v185, v85, v86
	v_sub_f32_e32 v85, v88, v195
	v_exp_f32_e32 v110, v85
	v_sub_f32_e32 v90, v90, v195
	v_exp_f32_e32 v164, v90
	v_sub_f32_e32 v90, v91, v195
	v_exp_f32_e32 v224, v90
	v_sub_f32_e32 v90, v92, v195
	v_exp_f32_e32 v226, v90
	v_sub_f32_e32 v90, v94, v195
	v_pk_mul_f32 v[48:49], v[48:49], v[208:209] op_sel_hi:[1,0]
	v_cvt_pk_bf16_f32 v84, v111, v165
	v_pk_add_f32 v[88:89], v[110:111], 0 op_sel_hi:[1,0]
	v_exp_f32_e32 v228, v90
	v_sub_f32_e32 v90, v109, v195
	v_cvt_pk_bf16_f32 v85, v225, v227
	v_cvt_pk_bf16_f32 v86, v229, v231
	v_cvt_pk_bf16_f32 v87, v93, v95
	v_pk_add_f32 v[88:89], v[164:165], v[88:89]
	v_mfma_f32_16x16x32_bf16 v[60:63], v[104:107], v[84:87], v[60:63]
	v_exp_f32_e32 v230, v90
	v_sub_f32_e32 v90, v160, v195
	v_pk_add_f32 v[88:89], v[224:225], v[88:89]
	v_mfma_f32_16x16x32_bf16 v[56:59], v[80:83], v[84:87], v[56:59]
	v_exp_f32_e32 v92, v90
	v_pk_add_f32 v[88:89], v[226:227], v[88:89]
	v_sub_f32_e32 v90, v161, v195
	v_mfma_f32_16x16x32_bf16 v[52:55], v[100:103], v[84:87], v[52:55]
	v_add_f32_e64 v88, v228, v88
	v_add_f32_e64 v89, v229, v89
	v_exp_f32_e32 v94, v90
	v_cvt_pk_bf16_f32 v220, v110, v164
	v_mfma_f32_16x16x32_bf16 v[48:51], v[96:99], v[84:87], v[48:51]
	v_sub_f32_e32 v84, v185, v195
	v_exp_f32_e32 v160, v84
	ds_read_b128 v[84:87], v108 offset:36864
	v_pk_add_f32 v[110:111], v[230:231], v[88:89]
	v_cvt_pk_bf16_f32 v223, v92, v94
	ds_read_b128 v[88:91], v108 offset:38912
	v_pk_add_f32 v[92:93], v[92:93], v[110:111]
	ds_read_b128 v[108:111], v162 offset:36864
	v_cvt_pk_bf16_f32 v221, v224, v226
	s_waitcnt lgkmcnt(2)
	v_mfma_f32_16x16x32_bf16 v[224:227], v[112:115], v[84:87], 0
	v_add_f32_e64 v164, v94, v92
	v_add_f32_e64 v165, v95, v93
	ds_bpermute_b32 v233, v187, v165
	ds_bpermute_b32 v232, v187, v164
	v_cvt_pk_bf16_f32 v222, v228, v230
	v_mfma_f32_16x16x32_bf16 v[228:231], v[116:119], v[84:87], 0
	ds_read_b128 v[92:95], v162 offset:38912
	v_cmp_le_i32_e64 s[4:5], v191, v173
	s_waitcnt lgkmcnt(1)
	v_pk_add_f32 v[162:163], v[164:165], v[232:233]
	v_mfma_f32_16x16x32_bf16 v[224:227], v[120:123], v[108:111], v[224:227]
	v_mov_b32_e32 v161, v208
	v_pk_mul_f32 v[46:47], v[46:47], v[160:161] op_sel_hi:[1,0]
	v_pk_mul_f32 v[44:45], v[44:45], v[160:161] op_sel_hi:[1,0]
	v_mfma_f32_16x16x32_bf16 v[228:231], v[124:127], v[108:111], v[228:231]
	v_mul_f32_e64 v38, v38, v160
	v_mul_f32_e64 v39, v39, v160
	s_nop 1
	v_add_f32_e32 v164, v234, v224
	v_cndmask_b32_e64 v185, v204, v164, s[4:5]
	v_add_f32_e32 v164, v235, v225
	v_cmp_lt_i32_e64 s[4:5], v191, v173
	v_add_f32_e32 v165, v236, v226
	v_mfma_f32_16x16x32_bf16 v[112:115], v[112:115], v[88:91], 0
	v_cndmask_b32_e64 v224, v204, v164, s[4:5]
	v_cmp_le_i32_e64 s[4:5], v219, v173
	v_max3_f32 v164, v185, s75, v224
	v_mfma_f32_16x16x32_bf16 v[116:119], v[116:119], v[88:91], 0
	v_cndmask_b32_e64 v225, v204, v165, s[4:5]
	v_add_f32_e32 v165, v237, v227
	v_cmp_le_i32_e64 s[4:5], v216, v173
	s_waitcnt lgkmcnt(0)
	v_mfma_f32_16x16x32_bf16 v[112:115], v[120:123], v[92:95], v[112:115]
	v_mul_f32_e64 v36, v36, v160
	v_mul_f32_e64 v37, v37, v160
	v_cndmask_b32_e64 v226, v204, v165, s[4:5]
	v_add_f32_e32 v165, v238, v228
	v_cmp_le_i32_e64 s[4:5], v218, v173
	v_max3_f32 v164, v164, v225, v226
	v_pk_mul_f32 v[34:35], v[34:35], v[160:161] op_sel_hi:[1,0]
	v_cndmask_b32_e64 v228, v204, v165, s[4:5]
	v_add_f32_e32 v165, v239, v229
	v_cmp_le_i32_e64 s[4:5], v215, v173
	v_pk_mul_f32 v[32:33], v[32:33], v[160:161] op_sel_hi:[1,0]
	v_pk_mul_f32 v[30:31], v[30:31], v[160:161] op_sel_hi:[1,0]
	v_cndmask_b32_e64 v232, v204, v165, s[4:5]
	v_add_f32_e32 v165, v240, v230
	v_cmp_le_i32_e64 s[4:5], v217, v173
	v_max3_f32 v164, v164, v228, v232
	v_pk_mul_f32 v[28:29], v[28:29], v[160:161] op_sel_hi:[1,0]
	v_cndmask_b32_e64 v230, v204, v165, s[4:5]
	v_add_f32_e32 v165, v241, v231
	v_cmp_le_i32_e64 s[4:5], v214, v173
	v_mfma_f32_16x16x32_bf16 v[116:119], v[124:127], v[92:95], v[116:119]
	v_add_f32_e32 v112, v242, v112
	v_cndmask_b32_e64 v235, v204, v165, s[4:5]
	v_max3_f32 v164, v164, v230, v235
	ds_bpermute_b32 v211, v187, v164
	v_cmp_le_i32_e64 s[4:5], v191, v174
	v_mfma_f32_16x16x32_bf16 v[44:47], v[104:107], v[220:223], v[44:47]
	v_or_b32_e32 v189, 34, v191
	v_cndmask_b32_e64 v123, v204, v112, s[4:5]
	s_waitcnt lgkmcnt(0)
	v_max_f32_e32 v211, v211, v211
	v_max_f32_e32 v211, v164, v211
	ds_bpermute_b32 v227, v149, v211
	v_mfma_f32_16x16x32_bf16 v[36:39], v[80:83], v[220:223], v[36:39]
	v_add_f32_e32 v112, v243, v113
	v_cmp_lt_i32_e64 s[4:5], v191, v174
	v_add_f32_e32 v113, v244, v114
	s_waitcnt lgkmcnt(0)
	v_max3_f32 v211, v167, v211, v227
	v_sub_f32_e32 v185, v185, v211
	v_mfma_f32_16x16x32_bf16 v[32:35], v[100:103], v[220:223], v[32:35]
	v_cndmask_b32_e64 v124, v204, v112, s[4:5]
	v_cmp_le_i32_e64 s[4:5], v219, v174
	v_sub_f32_e32 v167, v167, v211
	v_mfma_f32_16x16x32_bf16 v[28:31], v[96:99], v[220:223], v[28:31]
	v_exp_f32_e32 v221, v185
	v_sub_f32_e32 v185, v224, v211
	v_exp_f32_e32 v223, v185
	v_sub_f32_e32 v185, v225, v211
	v_exp_f32_e32 v225, v185
	v_sub_f32_e32 v185, v226, v211
	v_cndmask_b32_e64 v125, v204, v113, s[4:5]
	v_add_f32_e32 v113, v245, v115
	v_cmp_le_i32_e64 s[4:5], v216, v174
	v_exp_f32_e32 v227, v185
	v_sub_f32_e32 v185, v228, v211
	v_cndmask_b32_e64 v126, v204, v113, s[4:5]
	v_add_f32_e32 v113, v246, v116
	v_cmp_le_i32_e64 s[4:5], v218, v174
	v_exp_f32_e32 v229, v185
	v_sub_f32_e32 v185, v232, v211
	v_exp_f32_e32 v234, v167
	v_sub_f32_e32 v167, v235, v211
	v_cndmask_b32_e64 v127, v204, v113, s[4:5]
	v_add_f32_e32 v113, v247, v117
	v_cmp_le_i32_e64 s[4:5], v215, v174
	v_exp_f32_e32 v231, v185
	v_sub_f32_e32 v185, v230, v211
	v_exp_f32_e32 v237, v167
	v_max3_f32 v112, v123, s75, v124
	v_cndmask_b32_e64 v167, v204, v113, s[4:5]
	v_add_f32_e32 v113, v248, v118
	v_cmp_le_i32_e64 s[4:5], v217, v174
	v_exp_f32_e32 v233, v185
	v_max3_f32 v112, v112, v125, v126
	v_cndmask_b32_e64 v185, v204, v113, s[4:5]
	v_add_f32_e32 v113, v249, v119
	v_cmp_le_i32_e64 s[4:5], v214, v174
	v_max3_f32 v112, v112, v127, v167
	v_pk_mul_f32 v[42:43], v[42:43], v[234:235] op_sel_hi:[1,0]
	v_cndmask_b32_e64 v215, v204, v113, s[4:5]
	v_max3_f32 v116, v112, v185, v215
	ds_bpermute_b32 v117, v187, v116
	global_load_dwordx4 v[112:115], v[158:159], off offset:128
	v_pk_mul_f32 v[40:41], v[40:41], v[234:235] op_sel_hi:[1,0]
	v_pk_mul_f32 v[26:27], v[26:27], v[234:235] op_sel_hi:[1,0]
	v_pk_mul_f32 v[24:25], v[24:25], v[234:235] op_sel_hi:[1,0]
	s_waitcnt lgkmcnt(0)
	v_max_f32_e32 v117, v117, v117
	v_max_f32_e32 v116, v116, v117
	ds_bpermute_b32 v117, v149, v116
	v_pk_mul_f32 v[22:23], v[22:23], v[234:235] op_sel_hi:[1,0]
	v_pk_mul_f32 v[20:21], v[20:21], v[234:235] op_sel_hi:[1,0]
	v_pk_mul_f32 v[18:19], v[18:19], v[234:235] op_sel_hi:[1,0]
	v_pk_mul_f32 v[16:17], v[16:17], v[234:235] op_sel_hi:[1,0]
	s_waitcnt lgkmcnt(0)
	v_max3_f32 v214, v166, v116, v117
	v_sub_f32_e32 v116, v123, v214
	v_exp_f32_e32 v220, v116
	v_sub_f32_e32 v116, v124, v214
	v_exp_f32_e32 v222, v116
	global_load_dwordx4 v[116:119], v[158:159], off offset:192
	v_sub_f32_e32 v123, v125, v214
	v_exp_f32_e32 v224, v123
	v_sub_f32_e32 v126, v126, v214
	v_exp_f32_e32 v226, v126
	v_sub_f32_e32 v126, v127, v214
	v_cvt_pk_bf16_f32 v120, v221, v223
	v_pk_add_f32 v[124:125], v[220:221], 0 op_sel_hi:[1,0]
	v_exp_f32_e32 v228, v126
	v_sub_f32_e32 v126, v167, v214
	v_cvt_pk_bf16_f32 v121, v225, v227
	v_cvt_pk_bf16_f32 v122, v229, v231
	v_cvt_pk_bf16_f32 v123, v233, v237
	v_pk_add_f32 v[124:125], v[222:223], v[124:125]
	v_mfma_f32_16x16x32_bf16 v[40:43], v[104:107], v[120:123], v[40:43]
	v_exp_f32_e32 v230, v126
	v_pk_add_f32 v[124:125], v[224:225], v[124:125]
	v_mov_b32_e32 v159, v234
	v_mfma_f32_16x16x32_bf16 v[24:27], v[80:83], v[120:123], v[24:27]
	v_add_f32_e64 v124, v226, v124
	v_add_f32_e64 v125, v227, v125
	v_cvt_pk_bf16_f32 v126, v228, v230
	v_cmp_le_i32_e64 s[4:5], v192, v130
	v_mfma_f32_16x16x32_bf16 v[20:23], v[100:103], v[120:123], v[20:23]
	v_add_f32_e64 v124, v228, v124
	v_add_f32_e64 v125, v229, v125
	v_or_b32_e32 v188, 35, v191
	v_pk_add_f32 v[216:217], v[230:231], v[124:125]
	v_mfma_f32_16x16x32_bf16 v[16:19], v[96:99], v[120:123], v[16:19]
	v_sub_f32_e32 v120, v166, v214
	v_exp_f32_e32 v158, v120
	v_sub_f32_e32 v124, v185, v214
	v_exp_f32_e32 v232, v124
	v_sub_f32_e32 v124, v215, v214
	v_pk_mul_f32 v[14:15], v[14:15], v[158:159] op_sel_hi:[1,0]
	v_pk_mul_f32 v[12:13], v[12:13], v[158:159] op_sel_hi:[1,0]
	v_exp_f32_e32 v236, v124
	v_cvt_pk_bf16_f32 v124, v220, v222
	v_cvt_pk_bf16_f32 v125, v224, v226
	v_cvt_pk_bf16_f32 v127, v232, v236
	v_pk_mul_f32 v[2:3], v[2:3], v[158:159] op_sel_hi:[1,0]
	v_mfma_f32_16x16x32_bf16 v[12:15], v[104:107], v[124:127], v[12:15]
	ds_read_b128 v[104:107], v196 offset:4096
	ds_read_b128 v[120:123], v196 offset:6144
	v_pk_mul_f32 v[0:1], v[0:1], v[158:159] op_sel_hi:[1,0]
	v_pk_mul_f32 v[10:11], v[10:11], v[158:159] op_sel_hi:[1,0]
	v_pk_mul_f32 v[8:9], v[8:9], v[158:159] op_sel_hi:[1,0]
	v_mfma_f32_16x16x32_bf16 v[0:3], v[100:103], v[124:127], v[0:3]
	ds_read_b128 v[100:103], v194 offset:4096
	v_pk_mul_f32 v[6:7], v[6:7], v[158:159] op_sel_hi:[1,0]
	v_pk_mul_f32 v[4:5], v[4:5], v[158:159] op_sel_hi:[1,0]
	v_mfma_f32_16x16x32_bf16 v[8:11], v[80:83], v[124:127], v[8:11]
	v_or_b32_e32 v208, 49, v191
	v_pk_add_f32 v[166:167], v[232:233], v[216:217]
	ds_bpermute_b32 v165, v149, v163
	v_mfma_f32_16x16x32_bf16 v[4:7], v[96:99], v[124:127], v[4:7]
	ds_read_b128 v[124:127], v194 offset:6144
	v_pk_add_f32 v[166:167], v[236:237], v[166:167]
	ds_bpermute_b32 v164, v149, v162
	s_waitcnt lgkmcnt(5)
	v_mfma_f32_16x16x32_bf16 v[80:83], v[104:107], v[64:67], 0
	ds_bpermute_b32 v217, v187, v167
	ds_bpermute_b32 v216, v187, v166
	v_or_b32_e32 v191, 51, v191
	s_waitcnt lgkmcnt(6)
	v_mfma_f32_16x16x32_bf16 v[96:99], v[120:123], v[64:67], 0
	s_waitcnt lgkmcnt(2)
	v_pk_add_f32 v[162:163], v[162:163], v[164:165]
	s_waitcnt lgkmcnt(0)
	v_pk_add_f32 v[164:165], v[166:167], v[216:217]
	v_mfma_f32_16x16x32_bf16 v[80:83], v[100:103], v[76:79], v[80:83]
	ds_read2st64_b64 v[64:67], v186 offset0:16 offset1:20
	ds_read2st64_b64 v[216:219], v210 offset0:16 offset1:20
	ds_bpermute_b32 v167, v149, v165
	ds_bpermute_b32 v166, v149, v164
	v_mfma_f32_16x16x32_bf16 v[76:79], v[124:127], v[76:79], v[96:99]
	s_waitcnt vmcnt(1)
	s_nop 1
	v_sub_f32_e32 v96, v131, v112
	v_add_f32_e32 v80, v96, v80
	v_cndmask_b32_e64 v185, v204, v80, s[4:5]
	v_sub_f32_e32 v80, v131, v113
	v_add_f32_e32 v80, v80, v81
	v_cmp_le_i32_e64 s[4:5], v190, v130
	v_sub_f32_e32 v81, v131, v114
	v_add_f32_e32 v81, v81, v82
	v_cndmask_b32_e64 v194, v204, v80, s[4:5]
	v_cmp_le_i32_e64 s[4:5], v189, v130
	v_max3_f32 v80, v185, s75, v194
	s_waitcnt lgkmcnt(3)
	v_mov_b32_e32 v96, v66
	v_cndmask_b32_e64 v196, v204, v81, s[4:5]
	v_sub_f32_e32 v81, v131, v115
	v_add_f32_e32 v81, v81, v83
	v_cmp_le_i32_e64 s[4:5], v188, v130
	v_mov_b32_e32 v97, v67
	s_waitcnt lgkmcnt(2)
	v_mov_b32_e32 v67, v217
	v_cndmask_b32_e64 v215, v204, v81, s[4:5]
	s_waitcnt vmcnt(0)
	v_sub_f32_e32 v81, v131, v116
	v_add_f32_e32 v76, v81, v76
	v_cmp_le_i32_e64 s[4:5], v193, v130
	v_max3_f32 v80, v80, v196, v215
	s_nop 0
	v_cndmask_b32_e64 v220, v204, v76, s[4:5]
	v_sub_f32_e32 v76, v131, v117
	v_add_f32_e32 v76, v76, v77
	v_cmp_le_i32_e64 s[4:5], v208, v130
	v_sub_f32_e32 v77, v131, v118
	v_add_f32_e32 v77, v77, v78
	v_cndmask_b32_e64 v222, v204, v76, s[4:5]
	v_cmp_le_i32_e64 s[4:5], v197, v130
	v_max3_f32 v76, v80, v220, v222
	s_nop 0
	v_cndmask_b32_e64 v224, v204, v77, s[4:5]
	v_sub_f32_e32 v77, v131, v119
	v_add_f32_e32 v77, v77, v79
	v_cmp_le_i32_e64 s[4:5], v191, v130
	s_nop 1
	v_cndmask_b32_e64 v226, v204, v77, s[4:5]
	v_max3_f32 v98, v76, v224, v226
	ds_bpermute_b32 v99, v187, v98
	ds_read_b64 v[80:81], v186 offset:12288
	ds_read_b64 v[82:83], v210 offset:12288
	ds_read_b64 v[76:77], v212 offset:8192
	ds_read_b64 v[78:79], v213 offset:8192
	v_cmp_le_i32_e64 s[4:5], v192, v172
	s_waitcnt lgkmcnt(4)
	v_max_f32_e32 v66, v99, v99
	v_max_f32_e32 v186, v98, v66
	v_mov_b32_e32 v98, v218
	v_mov_b32_e32 v99, v219
	v_mov_b32_e32 v66, v216
	v_mfma_f32_16x16x32_bf16 v[216:219], v[104:107], v[72:75], 0
	ds_bpermute_b32 v210, v149, v186
	s_waitcnt lgkmcnt(0)
	v_max3_f32 v186, v209, v186, v210
	v_mfma_f32_16x16x32_bf16 v[72:75], v[120:123], v[72:75], 0
	v_sub_f32_e32 v185, v185, v186
	v_exp_f32_e32 v213, v185
	v_sub_f32_e32 v185, v194, v186
	v_mfma_f32_16x16x32_bf16 v[216:219], v[100:103], v[68:71], v[216:219]
	v_exp_f32_e32 v221, v185
	v_sub_f32_e32 v185, v196, v186
	v_exp_f32_e32 v223, v185
	v_mfma_f32_16x16x32_bf16 v[68:71], v[124:127], v[68:71], v[72:75]
	v_sub_f32_e32 v185, v215, v186
	v_exp_f32_e32 v225, v185
	v_sub_f32_e32 v185, v220, v186
	v_sub_f32_e32 v72, v155, v112
	v_add_f32_e32 v72, v72, v216
	v_sub_f32_e32 v73, v155, v113
	v_cndmask_b32_e64 v72, v204, v72, s[4:5]
	v_add_f32_e32 v73, v73, v217
	v_cmp_le_i32_e64 s[4:5], v190, v172
	v_sub_f32_e32 v75, v155, v114
	v_add_f32_e32 v75, v75, v218
	v_cndmask_b32_e64 v73, v204, v73, s[4:5]
	v_cmp_le_i32_e64 s[4:5], v189, v172
	v_max3_f32 v74, v72, s75, v73
	v_exp_f32_e32 v227, v185
	v_cndmask_b32_e64 v194, v204, v75, s[4:5]
	v_sub_f32_e32 v75, v155, v115
	v_add_f32_e32 v75, v75, v219
	v_cmp_le_i32_e64 s[4:5], v188, v172
	v_sub_f32_e32 v185, v222, v186
	v_sub_f32_e32 v209, v209, v186
	v_cndmask_b32_e64 v196, v204, v75, s[4:5]
	v_sub_f32_e32 v75, v155, v116
	v_add_f32_e32 v68, v75, v68
	v_cmp_le_i32_e64 s[4:5], v193, v172
	v_sub_f32_e32 v75, v155, v117
	v_add_f32_e32 v69, v75, v69
	v_cndmask_b32_e64 v68, v204, v68, s[4:5]
	v_cmp_le_i32_e64 s[4:5], v208, v172
	v_max3_f32 v74, v74, v194, v196
	v_exp_f32_e32 v75, v185
	v_cndmask_b32_e64 v210, v204, v69, s[4:5]
	v_max3_f32 v69, v74, v68, v210
	v_sub_f32_e32 v74, v155, v118
	v_add_f32_e32 v70, v74, v70
	v_cmp_le_i32_e64 s[4:5], v197, v172
	s_nop 1
	v_cndmask_b32_e64 v215, v204, v70, s[4:5]
	v_sub_f32_e32 v70, v155, v119
	v_add_f32_e32 v70, v70, v71
	v_cmp_le_i32_e64 s[4:5], v191, v172
	v_sub_f32_e32 v71, v224, v186
	v_exp_f32_e32 v229, v71
	v_cndmask_b32_e64 v218, v204, v70, s[4:5]
	v_max3_f32 v69, v69, v215, v218
	ds_bpermute_b32 v70, v187, v69
	v_sub_f32_e32 v71, v226, v186
	v_exp_f32_e32 v231, v71
	v_cvt_pk_bf16_f32 v71, v223, v225
	v_cmp_le_i32_e64 s[4:5], v190, v173
	s_waitcnt lgkmcnt(0)
	v_max_f32_e32 v70, v70, v70
	v_max_f32_e32 v74, v69, v70
	ds_bpermute_b32 v185, v149, v74
	v_exp_f32_e32 v69, v209
	v_cvt_pk_bf16_f32 v70, v213, v221
	s_waitcnt lgkmcnt(0)
	v_max3_f32 v185, v195, v74, v185
	v_sub_f32_e32 v72, v72, v185
	v_exp_f32_e32 v212, v72
	v_sub_f32_e32 v72, v73, v185
	v_exp_f32_e32 v220, v72
	v_sub_f32_e32 v74, v194, v185
	v_exp_f32_e32 v222, v74
	v_pk_add_f32 v[216:217], v[212:213], 0 op_sel_hi:[1,0]
	v_mov_b32_e32 v194, v69
	v_pk_add_f32 v[232:233], v[220:221], v[216:217]
	v_sub_f32_e32 v74, v196, v185
	v_pk_mul_f32 v[62:63], v[62:63], v[194:195] op_sel_hi:[1,0]
	v_pk_mul_f32 v[60:61], v[60:61], v[194:195] op_sel_hi:[1,0]
	v_pk_mul_f32 v[58:59], v[58:59], v[194:195] op_sel_hi:[1,0]
	v_pk_mul_f32 v[56:57], v[56:57], v[194:195] op_sel_hi:[1,0]
	v_pk_mul_f32 v[54:55], v[54:55], v[194:195] op_sel_hi:[1,0]
	v_pk_mul_f32 v[52:53], v[52:53], v[194:195] op_sel_hi:[1,0]
	v_pk_mul_f32 v[50:51], v[50:51], v[194:195] op_sel_hi:[1,0]
	v_pk_mul_f32 v[48:49], v[48:49], v[194:195] op_sel_hi:[1,0]
	v_cvt_pk_bf16_f32 v72, v227, v75
	v_cvt_pk_bf16_f32 v73, v229, v231
	v_exp_f32_e32 v224, v74
	v_sub_f32_e32 v68, v68, v185
	v_mfma_f32_16x16x32_bf16 v[60:63], v[64:67], v[70:73], v[60:63]
	v_cvt_pk_bf16_f32 v216, v212, v220
	v_cvt_pk_bf16_f32 v217, v222, v224
	v_exp_f32_e32 v226, v68
	v_mfma_f32_16x16x32_bf16 v[56:59], v[96:99], v[70:73], v[56:59]
	v_sub_f32_e32 v68, v210, v185
	v_exp_f32_e32 v74, v68
	v_sub_f32_e32 v68, v215, v185
	v_mfma_f32_16x16x32_bf16 v[52:55], v[80:83], v[70:73], v[52:55]
	v_exp_f32_e32 v228, v68
	v_sub_f32_e32 v68, v218, v185
	v_exp_f32_e32 v230, v68
	v_mfma_f32_16x16x32_bf16 v[48:51], v[76:79], v[70:73], v[48:51]
	v_add_f32_e64 v70, v222, v232
	v_add_f32_e64 v71, v223, v233
	v_pk_fma_f32 v[72:73], v[156:157], v[160:161], v[162:163]
	v_pk_add_f32 v[70:71], v[224:225], v[70:71]
	v_mfma_f32_16x16x32_bf16 v[220:223], v[104:107], v[84:87], 0
	v_add_f32_e64 v70, v226, v70
	v_add_f32_e64 v71, v227, v71
	v_cvt_pk_bf16_f32 v218, v226, v74
	v_sub_f32_e32 v68, v195, v185
	v_mfma_f32_16x16x32_bf16 v[84:87], v[120:123], v[84:87], 0
	v_add_f32_e64 v70, v74, v70
	v_add_f32_e64 v71, v75, v71
	v_exp_f32_e32 v68, v68
	v_pk_add_f32 v[70:71], v[228:229], v[70:71]
	v_mfma_f32_16x16x32_bf16 v[160:163], v[100:103], v[108:111], v[220:223]
	v_add_f32_e64 v74, v230, v70
	v_add_f32_e64 v75, v231, v71
	v_pk_add_f32 v[70:71], v[164:165], v[166:167]
	ds_bpermute_b32 v195, v187, v75
	v_mfma_f32_16x16x32_bf16 v[84:87], v[124:127], v[108:111], v[84:87]
	v_sub_f32_e32 v109, v168, v113
	s_nop 1
	v_add_f32_e32 v109, v109, v161
	v_sub_f32_e32 v111, v168, v114
	v_pk_fma_f32 v[70:71], v[150:151], v[158:159], v[70:71]
	v_cndmask_b32_e64 v109, v204, v109, s[4:5]
	v_add_f32_e32 v111, v111, v162
	v_cmp_le_i32_e64 s[4:5], v189, v173
	v_sub_f32_e32 v150, v168, v115
	v_add_f32_e32 v150, v150, v163
	v_cndmask_b32_e64 v111, v204, v111, s[4:5]
	v_cmp_le_i32_e64 s[4:5], v188, v173
	v_sub_f32_e32 v108, v168, v112
	v_add_f32_e32 v108, v108, v160
	v_cndmask_b32_e64 v156, v204, v150, s[4:5]
	v_sub_f32_e32 v150, v168, v116
	v_add_f32_e32 v84, v150, v84
	v_cmp_le_i32_e64 s[4:5], v193, v173
	v_cndmask_b32_e32 v108, v108, v204, vcc
	v_max3_f32 v110, v108, s75, v109
	v_cndmask_b32_e64 v157, v204, v84, s[4:5]
	v_sub_f32_e32 v84, v168, v117
	v_add_f32_e32 v84, v84, v85
	v_cmp_le_i32_e64 s[4:5], v208, v173
	v_sub_f32_e32 v85, v168, v118
	v_max3_f32 v110, v110, v111, v156
	v_cndmask_b32_e64 v158, v204, v84, s[4:5]
	v_add_f32_e32 v85, v85, v86
	v_cmp_le_i32_e64 s[4:5], v197, v173
	v_max3_f32 v84, v110, v157, v158
	ds_bpermute_b32 v194, v187, v74
	v_cndmask_b32_e64 v110, v204, v85, s[4:5]
	v_sub_f32_e32 v85, v168, v119
	v_add_f32_e32 v85, v85, v87
	v_cmp_le_i32_e64 s[4:5], v191, v173
	s_waitcnt lgkmcnt(0)
	v_pk_add_f32 v[74:75], v[74:75], v[194:195]
	ds_bpermute_b32 v151, v149, v75
	v_cndmask_b32_e64 v159, v204, v85, s[4:5]
	v_max3_f32 v84, v84, v110, v159
	ds_bpermute_b32 v85, v187, v84
	v_cmp_le_i32_e64 s[4:5], v192, v174
	ds_bpermute_b32 v150, v149, v74
	v_pk_mul_f32 v[46:47], v[46:47], v[68:69] op_sel_hi:[1,0]
	v_pk_mul_f32 v[44:45], v[44:45], v[68:69] op_sel_hi:[1,0]
	s_waitcnt lgkmcnt(1)
	v_max_f32_e32 v85, v85, v85
	v_max_f32_e32 v84, v84, v85
	ds_bpermute_b32 v85, v149, v84
	s_waitcnt lgkmcnt(1)
	v_pk_add_f32 v[74:75], v[74:75], v[150:151]
	v_pk_mul_f32 v[38:39], v[38:39], v[68:69] op_sel_hi:[1,0]
	v_pk_mul_f32 v[36:37], v[36:37], v[68:69] op_sel_hi:[1,0]
	v_pk_mul_f32 v[34:35], v[34:35], v[68:69] op_sel_hi:[1,0]
	s_waitcnt lgkmcnt(0)
	v_max3_f32 v167, v211, v84, v85
	v_mfma_f32_16x16x32_bf16 v[84:87], v[104:107], v[88:91], 0
	v_sub_f32_e32 v104, v108, v167
	v_exp_f32_e32 v105, v104
	v_sub_f32_e32 v104, v109, v167
	v_mfma_f32_16x16x32_bf16 v[88:91], v[120:123], v[88:91], 0
	v_exp_f32_e32 v107, v104
	v_sub_f32_e32 v104, v111, v167
	v_exp_f32_e32 v109, v104
	v_mfma_f32_16x16x32_bf16 v[84:87], v[100:103], v[92:95], v[84:87]
	v_sub_f32_e32 v100, v156, v167
	v_exp_f32_e32 v101, v100
	v_sub_f32_e32 v100, v157, v167
	v_mfma_f32_16x16x32_bf16 v[88:91], v[124:127], v[92:95], v[88:91]
	v_sub_f32_e32 v92, v169, v112
	s_nop 2
	v_add_f32_e32 v84, v92, v84
	v_sub_f32_e32 v92, v169, v113
	v_sub_f32_e32 v93, v169, v114
	v_cndmask_b32_e64 v84, v204, v84, s[4:5]
	v_add_f32_e32 v85, v92, v85
	v_cmp_le_i32_e64 s[4:5], v190, v174
	v_add_f32_e32 v86, v93, v86
	v_sub_f32_e32 v93, v169, v115
	v_cndmask_b32_e64 v85, v204, v85, s[4:5]
	v_cmp_le_i32_e64 s[4:5], v189, v174
	v_add_f32_e32 v87, v93, v87
	v_sub_f32_e32 v93, v169, v116
	v_cndmask_b32_e64 v86, v204, v86, s[4:5]
	v_cmp_le_i32_e64 s[4:5], v188, v174
	v_add_f32_e32 v88, v93, v88
	v_sub_f32_e32 v93, v169, v117
	v_max3_f32 v92, v84, s75, v85
	v_cndmask_b32_e64 v87, v204, v87, s[4:5]
	v_cndmask_b32_e32 v88, v88, v204, vcc
	v_add_f32_e32 v89, v93, v89
	v_cmp_le_i32_e32 vcc, v208, v174
	v_max3_f32 v92, v92, v86, v87
	v_sub_f32_e32 v95, v110, v167
	v_cndmask_b32_e32 v94, v204, v89, vcc
	v_max3_f32 v89, v92, v88, v94
	v_sub_f32_e32 v92, v169, v118
	v_add_f32_e32 v90, v92, v90
	v_cmp_le_i32_e32 vcc, v197, v174
	v_sub_f32_e32 v150, v211, v167
	v_exp_f32_e32 v103, v150
	v_cndmask_b32_e32 v92, v204, v90, vcc
	v_sub_f32_e32 v90, v169, v119
	v_add_f32_e32 v90, v90, v91
	v_cmp_le_i32_e32 vcc, v191, v174
	v_sub_f32_e32 v91, v158, v167
	v_exp_f32_e32 v91, v91
	v_cndmask_b32_e32 v102, v204, v90, vcc
	v_max3_f32 v90, v89, v92, v102
	ds_bpermute_b32 v93, v187, v90
	v_exp_f32_e32 v89, v100
	v_mov_b32_e32 v114, v103
	v_pk_mul_f32 v[32:33], v[32:33], v[68:69] op_sel_hi:[1,0]
	v_pk_mul_f32 v[30:31], v[30:31], v[68:69] op_sel_hi:[1,0]
	s_waitcnt lgkmcnt(0)
	v_max_f32_e32 v93, v93, v93
	v_max_f32_e32 v90, v90, v93
	ds_bpermute_b32 v100, v149, v90
	v_exp_f32_e32 v93, v95
	v_sub_f32_e32 v95, v159, v167
	v_exp_f32_e32 v95, v95
	v_pk_mul_f32 v[28:29], v[28:29], v[68:69] op_sel_hi:[1,0]
	s_waitcnt lgkmcnt(0)
	v_max3_f32 v166, v214, v90, v100
	v_sub_f32_e32 v84, v84, v166
	v_exp_f32_e32 v104, v84
	v_sub_f32_e32 v84, v85, v166
	v_exp_f32_e32 v106, v84
	v_sub_f32_e32 v84, v86, v166
	v_exp_f32_e32 v108, v84
	v_sub_f32_e32 v84, v87, v166
	v_exp_f32_e32 v100, v84
	v_sub_f32_e32 v86, v88, v166
	v_pk_add_f32 v[84:85], v[104:105], 0 op_sel_hi:[1,0]
	v_exp_f32_e32 v88, v86
	v_sub_f32_e32 v86, v94, v166
	v_pk_add_f32 v[84:85], v[106:107], v[84:85]
	v_exp_f32_e32 v90, v86
	v_sub_f32_e32 v86, v92, v166
	v_pk_add_f32 v[84:85], v[108:109], v[84:85]
	v_exp_f32_e32 v92, v86
	v_sub_f32_e32 v86, v102, v166
	v_pk_add_f32 v[84:85], v[100:101], v[84:85]
	v_exp_f32_e32 v94, v86
	v_pk_add_f32 v[84:85], v[88:89], v[84:85]
	v_cvt_pk_bf16_f32 v86, v89, v91
	v_sub_f32_e32 v89, v214, v166
	v_pk_add_f32 v[84:85], v[90:91], v[84:85]
	v_exp_f32_e32 v102, v89
	v_pk_add_f32 v[84:85], v[92:93], v[84:85]
	v_cvt_pk_bf16_f32 v87, v93, v95
	v_pk_mul_f32 v[42:43], v[42:43], v[114:115] op_sel_hi:[1,0]
	v_pk_add_f32 v[110:111], v[94:95], v[84:85]
	ds_bpermute_b32 v113, v187, v111
	ds_bpermute_b32 v112, v187, v110
	v_cvt_pk_bf16_f32 v84, v105, v107
	v_cvt_pk_bf16_f32 v85, v109, v101
	v_pk_mul_f32 v[40:41], v[40:41], v[114:115] op_sel_hi:[1,0]
	v_pk_mul_f32 v[26:27], v[26:27], v[114:115] op_sel_hi:[1,0]
	s_waitcnt lgkmcnt(0)
	v_pk_add_f32 v[110:111], v[110:111], v[112:113]
	ds_bpermute_b32 v113, v149, v111
	ds_bpermute_b32 v112, v149, v110
	v_pk_mul_f32 v[24:25], v[24:25], v[114:115] op_sel_hi:[1,0]
	v_pk_mul_f32 v[22:23], v[22:23], v[114:115] op_sel_hi:[1,0]
	v_pk_mul_f32 v[20:21], v[20:21], v[114:115] op_sel_hi:[1,0]
	v_pk_mul_f32 v[18:19], v[18:19], v[114:115] op_sel_hi:[1,0]
	v_pk_mul_f32 v[16:17], v[16:17], v[114:115] op_sel_hi:[1,0]
	v_pk_mul_f32 v[14:15], v[14:15], v[102:103] op_sel_hi:[1,0]
	v_pk_mul_f32 v[12:13], v[12:13], v[102:103] op_sel_hi:[1,0]
	v_pk_mul_f32 v[10:11], v[10:11], v[102:103] op_sel_hi:[1,0]
	v_pk_mul_f32 v[8:9], v[8:9], v[102:103] op_sel_hi:[1,0]
	v_pk_mul_f32 v[2:3], v[2:3], v[102:103] op_sel_hi:[1,0]
	v_pk_mul_f32 v[0:1], v[0:1], v[102:103] op_sel_hi:[1,0]
	v_pk_mul_f32 v[6:7], v[6:7], v[102:103] op_sel_hi:[1,0]
	v_pk_mul_f32 v[4:5], v[4:5], v[102:103] op_sel_hi:[1,0]
	v_cvt_pk_bf16_f32 v219, v228, v230
	v_mfma_f32_16x16x32_bf16 v[40:43], v[64:67], v[84:87], v[40:43]
	v_fma_f32 v156, v72, v68, v74
	v_fma_f32 v157, v73, v69, v75
	v_mfma_f32_16x16x32_bf16 v[44:47], v[64:67], v[216:219], v[44:47]
	v_mfma_f32_16x16x32_bf16 v[36:39], v[96:99], v[216:219], v[36:39]
	v_mfma_f32_16x16x32_bf16 v[32:35], v[80:83], v[216:219], v[32:35]
	v_mfma_f32_16x16x32_bf16 v[28:31], v[76:79], v[216:219], v[28:31]
	v_mfma_f32_16x16x32_bf16 v[24:27], v[96:99], v[84:87], v[24:27]
	v_mfma_f32_16x16x32_bf16 v[20:23], v[80:83], v[84:87], v[20:23]
	v_mfma_f32_16x16x32_bf16 v[16:19], v[76:79], v[84:87], v[16:19]
	v_cvt_pk_bf16_f32 v84, v104, v106
	v_cvt_pk_bf16_f32 v85, v108, v100
	v_cvt_pk_bf16_f32 v86, v88, v90
	v_cvt_pk_bf16_f32 v87, v92, v94
	s_nop 0
	v_mfma_f32_16x16x32_bf16 v[12:15], v[64:67], v[84:87], v[12:15]
	s_waitcnt lgkmcnt(0)
	v_pk_add_f32 v[64:65], v[110:111], v[112:113]
	s_nop 0
	v_pk_fma_f32 v[150:151], v[70:71], v[102:103], v[64:65]
	v_mfma_f32_16x16x32_bf16 v[8:11], v[96:99], v[84:87], v[8:11]
	v_mfma_f32_16x16x32_bf16 v[0:3], v[80:83], v[84:87], v[0:3]
	v_mfma_f32_16x16x32_bf16 v[4:7], v[76:79], v[84:87], v[4:7]

.Lfoxf_fast:
	s_lshl_b32 s84, s23, 6
	v_lshl_add_u64 v[158:159], s[84:85], 2, v[146:147]
	global_load_dwordx4 v[224:227], v[158:159], off
	global_load_dwordx4 v[228:231], v[158:159], off offset:64
	global_load_dwordx4 v[232:235], v[158:159], off offset:128
	global_load_dwordx4 v[236:239], v[158:159], off offset:192
	s_lshl_b32 s4, s21, 14
	v_or_b32_e32 v193, s4, v178
	v_add_u32_e32 v248, v193, v176
	v_add_u32_e32 v249, v193, v177
	v_add_u32_e32 v191, v175, v176
	v_add_u32_e32 v192, v175, v177
	v_add_u32_e32 v187, v193, v181
	v_add_u32_e32 v188, v193, v182
	v_add_u32_e32 v189, v193, v183
	v_add_u32_e32 v190, v193, v184
	ds_read_b128 v[64:67], v248
	ds_read_b128 v[68:71], v248 offset:2048
	ds_read_b128 v[72:75], v249
	ds_read_b128 v[76:79], v249 offset:2048
	ds_read_b128 v[96:99], v191 offset:32768
	ds_read_b128 v[100:103], v192 offset:32768
	ds_read_b128 v[104:107], v191 offset:34816
	ds_read_b128 v[108:111], v192 offset:34816
	ds_read_b64 v[80:81], v187 offset:8192
	ds_read_b64 v[82:83], v188 offset:8192
	ds_read_b64 v[84:85], v187 offset:10240
	ds_read_b64 v[86:87], v188 offset:10240
	ds_read_b64 v[88:89], v187 offset:12288
	ds_read_b64 v[90:91], v188 offset:12288
	ds_read_b64 v[92:93], v187 offset:14336
	ds_read_b64 v[94:95], v188 offset:14336
	s_waitcnt lgkmcnt(8)
	v_mfma_f32_16x16x32_bf16 v[112:115], v[64:67], v[96:99], 0
	v_mfma_f32_16x16x32_bf16 v[116:119], v[68:71], v[96:99], 0
	v_mfma_f32_16x16x32_bf16 v[120:123], v[64:67], v[104:107], 0
	v_mfma_f32_16x16x32_bf16 v[124:127], v[68:71], v[104:107], 0
	v_mfma_f32_16x16x32_bf16 v[112:115], v[72:75], v[100:103], v[112:115]
	v_mfma_f32_16x16x32_bf16 v[116:119], v[76:79], v[100:103], v[116:119]
	v_mfma_f32_16x16x32_bf16 v[120:123], v[72:75], v[108:111], v[120:123]
	v_mfma_f32_16x16x32_bf16 v[124:127], v[76:79], v[108:111], v[124:127]
	ds_read_b128 v[96:99], v191 offset:36864
	ds_read_b128 v[100:103], v192 offset:36864
	ds_read_b128 v[104:107], v191 offset:38912
	ds_read_b128 v[108:111], v192 offset:38912
	s_waitcnt vmcnt(2)
	s_waitcnt lgkmcnt(0)
	v_mfma_f32_16x16x32_bf16 v[208:211], v[64:67], v[96:99], 0
	v_sub_f32_e32 v112, v112, v224
	v_sub_f32_e32 v113, v113, v225
	v_sub_f32_e32 v114, v114, v226
	v_sub_f32_e32 v115, v115, v227
	v_sub_f32_e32 v116, v116, v228
	v_sub_f32_e32 v117, v117, v229
	v_sub_f32_e32 v118, v118, v230
	v_sub_f32_e32 v119, v119, v231
	v_sub_f32_e32 v120, v120, v224
	v_sub_f32_e32 v121, v121, v225
	v_sub_f32_e32 v122, v122, v226
	v_sub_f32_e32 v123, v123, v227
	v_mfma_f32_16x16x32_bf16 v[212:215], v[68:71], v[96:99], 0
	v_sub_f32_e32 v124, v124, v228
	v_sub_f32_e32 v125, v125, v229
	v_sub_f32_e32 v126, v126, v230
	v_sub_f32_e32 v127, v127, v231
	v_max3_f32 v240, v112, v113, v114
	v_max3_f32 v240, v240, v115, v116
	v_max3_f32 v240, v240, v117, v118
	v_max_f32_e32 v240, v240, v119
	v_max3_f32 v241, v120, v121, v122
	v_max3_f32 v241, v241, v123, v124
	v_max3_f32 v241, v241, v125, v126
	v_max_f32_e32 v241, v241, v127
	v_mfma_f32_16x16x32_bf16 v[216:219], v[64:67], v[104:107], 0
	v_add_f32_e32 v240, v240, v131
	v_add_f32_e32 v241, v241, v155
	v_mov_b32_e32 v242, v240
	v_mov_b32_e32 v243, v241
	s_nop 1
	v_permlane16_swap_b32_e32 v240, v242
	v_permlane16_swap_b32_e32 v241, v243
	v_max_f32_e32 v240, v240, v242
	v_max_f32_e32 v241, v241, v243
	v_mov_b32_e32 v242, v240
	v_mov_b32_e32 v243, v241
	s_nop 1
	v_permlane32_swap_b32_e32 v240, v242
	v_permlane32_swap_b32_e32 v241, v243
	v_max3_f32 v240, v186, v240, v242
	v_sub_f32_e32 v244, v186, v240
	v_sub_f32_e32 v246, v240, v131
	v_exp_f32_e32 v244, v244
	v_mov_b32_e32 v186, v240
	v_max3_f32 v241, v185, v241, v243
	v_sub_f32_e32 v245, v185, v241
	v_sub_f32_e32 v247, v241, v155
	v_exp_f32_e32 v245, v245
	v_mov_b32_e32 v185, v241
	v_mfma_f32_16x16x32_bf16 v[220:223], v[68:71], v[104:107], 0
	v_sub_f32_e32 v112, v112, v246
	v_sub_f32_e32 v113, v113, v246
	v_sub_f32_e32 v114, v114, v246
	v_sub_f32_e32 v115, v115, v246
	v_sub_f32_e32 v116, v116, v246
	v_sub_f32_e32 v117, v117, v246
	v_sub_f32_e32 v118, v118, v246
	v_sub_f32_e32 v119, v119, v246
	v_sub_f32_e32 v120, v120, v247
	v_sub_f32_e32 v121, v121, v247
	v_sub_f32_e32 v122, v122, v247
	v_mfma_f32_16x16x32_bf16 v[208:211], v[72:75], v[100:103], v[208:211]
	v_sub_f32_e32 v123, v123, v247
	v_sub_f32_e32 v124, v124, v247
	v_sub_f32_e32 v125, v125, v247
	v_sub_f32_e32 v126, v126, v247
	v_sub_f32_e32 v127, v127, v247
	v_exp_f32_e32 v112, v112
	v_exp_f32_e32 v113, v113
	v_exp_f32_e32 v114, v114
	v_exp_f32_e32 v115, v115
	v_exp_f32_e32 v116, v116
	v_exp_f32_e32 v117, v117
	v_exp_f32_e32 v118, v118
	v_mfma_f32_16x16x32_bf16 v[212:215], v[76:79], v[100:103], v[212:215]
	v_exp_f32_e32 v119, v119
	v_exp_f32_e32 v120, v120
	v_exp_f32_e32 v121, v121
	v_exp_f32_e32 v122, v122
	v_exp_f32_e32 v123, v123
	v_exp_f32_e32 v124, v124
	v_exp_f32_e32 v125, v125
	v_exp_f32_e32 v126, v126
	v_exp_f32_e32 v127, v127
	v_add_f32_e32 v240, v112, v113
	v_add_f32_e32 v242, v114, v115
	v_add_f32_e32 v240, v240, v242
	v_mfma_f32_16x16x32_bf16 v[216:219], v[72:75], v[108:111], v[216:219]
	v_add_f32_e32 v242, v116, v117
	v_add_f32_e32 v240, v240, v242
	v_add_f32_e32 v242, v118, v119
	v_add_f32_e32 v240, v240, v242
	v_fma_f32 v157, v157, v244, v240
	v_add_f32_e32 v241, v120, v121
	v_add_f32_e32 v243, v122, v123
	v_add_f32_e32 v241, v241, v243
	v_add_f32_e32 v243, v124, v125
	v_add_f32_e32 v241, v241, v243
	v_add_f32_e32 v243, v126, v127
	v_add_f32_e32 v241, v241, v243
	v_mfma_f32_16x16x32_bf16 v[220:223], v[76:79], v[108:111], v[220:223]
	ds_read_b128 v[64:67], v248 offset:4096
	ds_read_b128 v[68:71], v248 offset:6144
	ds_read_b128 v[72:75], v249 offset:4096
	ds_read_b128 v[76:79], v249 offset:6144
	ds_read_b128 v[96:99], v191 offset:32768
	ds_read_b128 v[100:103], v192 offset:32768
	ds_read_b128 v[104:107], v191 offset:34816
	ds_read_b128 v[108:111], v192 offset:34816
	v_fma_f32 v156, v156, v245, v241
	v_cvt_pk_bf16_f32 v112, v112, v113
	v_cvt_pk_bf16_f32 v113, v114, v115
	v_cvt_pk_bf16_f32 v114, v116, v117
	v_cvt_pk_bf16_f32 v115, v118, v119
	v_cvt_pk_bf16_f32 v120, v120, v121
	v_cvt_pk_bf16_f32 v121, v122, v123
	v_cvt_pk_bf16_f32 v122, v124, v125
	v_cvt_pk_bf16_f32 v123, v126, v127
	v_cmp_neq_f32_e32 vcc, 1.0, v244
	s_nop 1
	s_cbranch_vccz .Lfoxf_r0
	v_mul_f32_e32 v60, v60, v244
	v_mul_f32_e32 v61, v61, v244
	v_mul_f32_e32 v62, v62, v244
	v_mul_f32_e32 v63, v63, v244
	v_mul_f32_e32 v56, v56, v244
	v_mul_f32_e32 v57, v57, v244
	v_mul_f32_e32 v58, v58, v244
	v_mul_f32_e32 v59, v59, v244
	v_mul_f32_e32 v52, v52, v244
	v_mul_f32_e32 v53, v53, v244
	v_mul_f32_e32 v54, v54, v244
	v_mul_f32_e32 v55, v55, v244
	v_mul_f32_e32 v48, v48, v244
	v_mul_f32_e32 v49, v49, v244
	v_mul_f32_e32 v50, v50, v244
	v_mul_f32_e32 v51, v51, v244
.Lfoxf_r0:
	v_cmp_neq_f32_e32 vcc, 1.0, v245
	s_nop 1
	s_cbranch_vccz .Lfoxf_r1
	v_mul_f32_e32 v44, v44, v245
	v_mul_f32_e32 v45, v45, v245
	v_mul_f32_e32 v46, v46, v245
	v_mul_f32_e32 v47, v47, v245
	v_mul_f32_e32 v36, v36, v245
	v_mul_f32_e32 v37, v37, v245
	v_mul_f32_e32 v38, v38, v245
	v_mul_f32_e32 v39, v39, v245
	v_mul_f32_e32 v32, v32, v245
	v_mul_f32_e32 v33, v33, v245
	v_mul_f32_e32 v34, v34, v245
	v_mul_f32_e32 v35, v35, v245
	v_mul_f32_e32 v28, v28, v245
	v_mul_f32_e32 v29, v29, v245
	v_mul_f32_e32 v30, v30, v245
	v_mul_f32_e32 v31, v31, v245
.Lfoxf_r1:
	s_waitcnt lgkmcnt(12)
	v_mfma_f32_16x16x32_bf16 v[60:63], v[80:83], v[112:115], v[60:63]
	v_sub_f32_e32 v208, v208, v224
	v_sub_f32_e32 v209, v209, v225
	v_sub_f32_e32 v210, v210, v226
	v_sub_f32_e32 v211, v211, v227
	v_sub_f32_e32 v212, v212, v228
	v_sub_f32_e32 v213, v213, v229
	v_mfma_f32_16x16x32_bf16 v[44:47], v[80:83], v[120:123], v[44:47]
	v_sub_f32_e32 v214, v214, v230
	v_sub_f32_e32 v215, v215, v231
	v_sub_f32_e32 v216, v216, v224
	v_sub_f32_e32 v217, v217, v225
	v_sub_f32_e32 v218, v218, v226
	v_sub_f32_e32 v219, v219, v227
	v_mfma_f32_16x16x32_bf16 v[56:59], v[84:87], v[112:115], v[56:59]
	v_sub_f32_e32 v220, v220, v228
	v_sub_f32_e32 v221, v221, v229
	v_sub_f32_e32 v222, v222, v230
	v_sub_f32_e32 v223, v223, v231
	v_max3_f32 v240, v208, v209, v210
	v_max3_f32 v240, v240, v211, v212
	v_mfma_f32_16x16x32_bf16 v[36:39], v[84:87], v[120:123], v[36:39]
	v_max3_f32 v240, v240, v213, v214
	v_max_f32_e32 v240, v240, v215
	v_max3_f32 v241, v216, v217, v218
	v_max3_f32 v241, v241, v219, v220
	v_max3_f32 v241, v241, v221, v222
	v_max_f32_e32 v241, v241, v223
	v_mfma_f32_16x16x32_bf16 v[52:55], v[88:91], v[112:115], v[52:55]
	v_add_f32_e32 v240, v240, v168
	v_add_f32_e32 v241, v241, v169
	v_mov_b32_e32 v242, v240
	v_mov_b32_e32 v243, v241
	s_nop 1
	v_permlane16_swap_b32_e32 v240, v242
	v_permlane16_swap_b32_e32 v241, v243
	v_max_f32_e32 v240, v240, v242
	v_max_f32_e32 v241, v241, v243
	v_mov_b32_e32 v242, v240
	v_mov_b32_e32 v243, v241
	s_nop 1
	v_permlane32_swap_b32_e32 v240, v242
	v_permlane32_swap_b32_e32 v241, v243
	v_max3_f32 v240, v167, v240, v242
	v_sub_f32_e32 v244, v167, v240
	v_sub_f32_e32 v246, v240, v168
	v_exp_f32_e32 v244, v244
	v_mfma_f32_16x16x32_bf16 v[32:35], v[88:91], v[120:123], v[32:35]
	v_mov_b32_e32 v167, v240
	v_max3_f32 v241, v166, v241, v243
	v_sub_f32_e32 v245, v166, v241
	v_sub_f32_e32 v247, v241, v169
	v_exp_f32_e32 v245, v245
	v_mov_b32_e32 v166, v241
	v_mfma_f32_16x16x32_bf16 v[48:51], v[92:95], v[112:115], v[48:51]
	v_sub_f32_e32 v208, v208, v246
	v_sub_f32_e32 v209, v209, v246
	v_sub_f32_e32 v210, v210, v246
	v_sub_f32_e32 v211, v211, v246
	v_sub_f32_e32 v212, v212, v246
	v_sub_f32_e32 v213, v213, v246
	v_mfma_f32_16x16x32_bf16 v[28:31], v[92:95], v[120:123], v[28:31]
	v_sub_f32_e32 v214, v214, v246
	v_sub_f32_e32 v215, v215, v246
	v_sub_f32_e32 v216, v216, v247
	v_sub_f32_e32 v217, v217, v247
	v_sub_f32_e32 v218, v218, v247
	s_waitcnt lgkmcnt(0)
	v_mfma_f32_16x16x32_bf16 v[112:115], v[64:67], v[96:99], 0
	v_sub_f32_e32 v219, v219, v247
	v_sub_f32_e32 v220, v220, v247
	v_sub_f32_e32 v221, v221, v247
	v_sub_f32_e32 v222, v222, v247
	v_sub_f32_e32 v223, v223, v247
	v_exp_f32_e32 v208, v208
	v_mfma_f32_16x16x32_bf16 v[116:119], v[68:71], v[96:99], 0
	v_exp_f32_e32 v209, v209
	v_exp_f32_e32 v210, v210
	v_exp_f32_e32 v211, v211
	v_exp_f32_e32 v212, v212
	v_exp_f32_e32 v213, v213
	v_exp_f32_e32 v214, v214
	v_mfma_f32_16x16x32_bf16 v[120:123], v[64:67], v[104:107], 0
	v_exp_f32_e32 v215, v215
	v_exp_f32_e32 v216, v216
	v_exp_f32_e32 v217, v217
	v_exp_f32_e32 v218, v218
	v_exp_f32_e32 v219, v219
	v_exp_f32_e32 v220, v220
	v_mfma_f32_16x16x32_bf16 v[124:127], v[68:71], v[104:107], 0
	v_exp_f32_e32 v221, v221
	v_exp_f32_e32 v222, v222
	v_exp_f32_e32 v223, v223
	v_add_f32_e32 v240, v208, v209
	v_add_f32_e32 v242, v210, v211
	v_add_f32_e32 v240, v240, v242
	v_mfma_f32_16x16x32_bf16 v[112:115], v[72:75], v[100:103], v[112:115]
	v_add_f32_e32 v242, v212, v213
	v_add_f32_e32 v240, v240, v242
	v_add_f32_e32 v242, v214, v215
	v_add_f32_e32 v240, v240, v242
	v_fma_f32 v151, v151, v244, v240
	v_add_f32_e32 v241, v216, v217
	v_mfma_f32_16x16x32_bf16 v[116:119], v[76:79], v[100:103], v[116:119]
	v_add_f32_e32 v243, v218, v219
	v_add_f32_e32 v241, v241, v243
	v_add_f32_e32 v243, v220, v221
	v_add_f32_e32 v241, v241, v243
	v_add_f32_e32 v243, v222, v223
	v_add_f32_e32 v241, v241, v243
	v_mfma_f32_16x16x32_bf16 v[120:123], v[72:75], v[108:111], v[120:123]
	v_fma_f32 v150, v150, v245, v241
	v_cvt_pk_bf16_f32 v208, v208, v209
	v_cvt_pk_bf16_f32 v209, v210, v211
	v_cvt_pk_bf16_f32 v210, v212, v213
	v_cvt_pk_bf16_f32 v211, v214, v215
	v_cvt_pk_bf16_f32 v216, v216, v217
	v_mfma_f32_16x16x32_bf16 v[124:127], v[76:79], v[108:111], v[124:127]
	ds_read_b128 v[96:99], v191 offset:36864
	ds_read_b128 v[100:103], v192 offset:36864
	ds_read_b128 v[104:107], v191 offset:38912
	ds_read_b128 v[108:111], v192 offset:38912
	v_cvt_pk_bf16_f32 v217, v218, v219
	v_cvt_pk_bf16_f32 v218, v220, v221
	v_cvt_pk_bf16_f32 v219, v222, v223
	v_cmp_neq_f32_e32 vcc, 1.0, v244
	s_nop 1
	s_cbranch_vccz .Lfoxf_r2
	v_mul_f32_e32 v40, v40, v244
	v_mul_f32_e32 v41, v41, v244
	v_mul_f32_e32 v42, v42, v244
	v_mul_f32_e32 v43, v43, v244
	v_mul_f32_e32 v24, v24, v244
	v_mul_f32_e32 v25, v25, v244
	v_mul_f32_e32 v26, v26, v244
	v_mul_f32_e32 v27, v27, v244
	v_mul_f32_e32 v20, v20, v244
	v_mul_f32_e32 v21, v21, v244
	v_mul_f32_e32 v22, v22, v244
	v_mul_f32_e32 v23, v23, v244
	v_mul_f32_e32 v16, v16, v244
	v_mul_f32_e32 v17, v17, v244
	v_mul_f32_e32 v18, v18, v244
	v_mul_f32_e32 v19, v19, v244
.Lfoxf_r2:
	v_cmp_neq_f32_e32 vcc, 1.0, v245
	s_nop 1
	s_cbranch_vccz .Lfoxf_r3
	v_mul_f32_e32 v12, v12, v245
	v_mul_f32_e32 v13, v13, v245
	v_mul_f32_e32 v14, v14, v245
	v_mul_f32_e32 v15, v15, v245
	v_mul_f32_e32 v8, v8, v245
	v_mul_f32_e32 v9, v9, v245
	v_mul_f32_e32 v10, v10, v245
	v_mul_f32_e32 v11, v11, v245
	v_mul_f32_e32 v0, v0, v245
	v_mul_f32_e32 v1, v1, v245
	v_mul_f32_e32 v2, v2, v245
	v_mul_f32_e32 v3, v3, v245
	v_mul_f32_e32 v4, v4, v245
	v_mul_f32_e32 v5, v5, v245
	v_mul_f32_e32 v6, v6, v245
	v_mul_f32_e32 v7, v7, v245
.Lfoxf_r3:
	s_waitcnt vmcnt(0)
	v_mfma_f32_16x16x32_bf16 v[40:43], v[80:83], v[208:211], v[40:43]
	v_sub_f32_e32 v112, v112, v232
	v_sub_f32_e32 v113, v113, v233
	v_sub_f32_e32 v114, v114, v234
	v_sub_f32_e32 v115, v115, v235
	v_sub_f32_e32 v116, v116, v236
	v_sub_f32_e32 v117, v117, v237
	v_mfma_f32_16x16x32_bf16 v[12:15], v[80:83], v[216:219], v[12:15]
	v_sub_f32_e32 v118, v118, v238
	v_sub_f32_e32 v119, v119, v239
	v_sub_f32_e32 v120, v120, v232
	v_sub_f32_e32 v121, v121, v233
	v_sub_f32_e32 v122, v122, v234
	v_sub_f32_e32 v123, v123, v235
	v_mfma_f32_16x16x32_bf16 v[24:27], v[84:87], v[208:211], v[24:27]
	v_sub_f32_e32 v124, v124, v236
	v_sub_f32_e32 v125, v125, v237
	v_sub_f32_e32 v126, v126, v238
	v_sub_f32_e32 v127, v127, v239
	v_max3_f32 v240, v112, v113, v114
	v_max3_f32 v240, v240, v115, v116
	v_mfma_f32_16x16x32_bf16 v[8:11], v[84:87], v[216:219], v[8:11]
	v_max3_f32 v240, v240, v117, v118
	v_max_f32_e32 v240, v240, v119
	v_max3_f32 v241, v120, v121, v122
	v_max3_f32 v241, v241, v123, v124
	v_max3_f32 v241, v241, v125, v126
	v_max_f32_e32 v241, v241, v127
	v_mfma_f32_16x16x32_bf16 v[20:23], v[88:91], v[208:211], v[20:23]
	v_add_f32_e32 v240, v240, v131
	v_add_f32_e32 v241, v241, v155
	v_mov_b32_e32 v242, v240
	v_mov_b32_e32 v243, v241
	s_nop 1
	v_permlane16_swap_b32_e32 v240, v242
	v_permlane16_swap_b32_e32 v241, v243
	v_max_f32_e32 v240, v240, v242
	v_max_f32_e32 v241, v241, v243
	v_mov_b32_e32 v242, v240
	v_mov_b32_e32 v243, v241
	s_nop 1
	v_permlane32_swap_b32_e32 v240, v242
	v_permlane32_swap_b32_e32 v241, v243
	v_max3_f32 v240, v186, v240, v242
	v_sub_f32_e32 v244, v186, v240
	v_sub_f32_e32 v246, v240, v131
	v_exp_f32_e32 v244, v244
	v_mfma_f32_16x16x32_bf16 v[0:3], v[88:91], v[216:219], v[0:3]
	v_mov_b32_e32 v186, v240
	v_max3_f32 v241, v185, v241, v243
	v_sub_f32_e32 v245, v185, v241
	v_sub_f32_e32 v247, v241, v155
	v_exp_f32_e32 v245, v245
	v_mov_b32_e32 v185, v241
	v_mfma_f32_16x16x32_bf16 v[16:19], v[92:95], v[208:211], v[16:19]
	v_sub_f32_e32 v112, v112, v246
	v_sub_f32_e32 v113, v113, v246
	v_sub_f32_e32 v114, v114, v246
	v_sub_f32_e32 v115, v115, v246
	v_sub_f32_e32 v116, v116, v246
	v_sub_f32_e32 v117, v117, v246
	v_mfma_f32_16x16x32_bf16 v[4:7], v[92:95], v[216:219], v[4:7]
	v_sub_f32_e32 v118, v118, v246
	v_sub_f32_e32 v119, v119, v246
	v_sub_f32_e32 v120, v120, v247
	v_sub_f32_e32 v121, v121, v247
	v_sub_f32_e32 v122, v122, v247
	ds_read_b64 v[80:81], v189 offset:8192
	ds_read_b64 v[82:83], v190 offset:8192
	ds_read_b64 v[84:85], v189 offset:10240
	ds_read_b64 v[86:87], v190 offset:10240
	ds_read_b64 v[88:89], v189 offset:12288
	ds_read_b64 v[90:91], v190 offset:12288
	ds_read_b64 v[92:93], v189 offset:14336
	ds_read_b64 v[94:95], v190 offset:14336
	s_waitcnt lgkmcnt(8)
	v_mfma_f32_16x16x32_bf16 v[208:211], v[64:67], v[96:99], 0
	v_sub_f32_e32 v123, v123, v247
	v_sub_f32_e32 v124, v124, v247
	v_sub_f32_e32 v125, v125, v247
	v_sub_f32_e32 v126, v126, v247
	v_sub_f32_e32 v127, v127, v247
	v_exp_f32_e32 v112, v112
	v_mfma_f32_16x16x32_bf16 v[212:215], v[68:71], v[96:99], 0
	v_exp_f32_e32 v113, v113
	v_exp_f32_e32 v114, v114
	v_exp_f32_e32 v115, v115
	v_exp_f32_e32 v116, v116
	v_exp_f32_e32 v117, v117
	v_exp_f32_e32 v118, v118
	v_mfma_f32_16x16x32_bf16 v[216:219], v[64:67], v[104:107], 0
	v_exp_f32_e32 v119, v119
	v_exp_f32_e32 v120, v120
	v_exp_f32_e32 v121, v121
	v_exp_f32_e32 v122, v122
	v_exp_f32_e32 v123, v123
	v_exp_f32_e32 v124, v124
	v_mfma_f32_16x16x32_bf16 v[220:223], v[68:71], v[104:107], 0
	v_exp_f32_e32 v125, v125
	v_exp_f32_e32 v126, v126
	v_exp_f32_e32 v127, v127
	v_add_f32_e32 v240, v112, v113
	v_add_f32_e32 v242, v114, v115
	v_add_f32_e32 v240, v240, v242
	v_mfma_f32_16x16x32_bf16 v[208:211], v[72:75], v[100:103], v[208:211]
	v_add_f32_e32 v242, v116, v117
	v_add_f32_e32 v240, v240, v242
	v_add_f32_e32 v242, v118, v119
	v_add_f32_e32 v240, v240, v242
	v_fma_f32 v157, v157, v244, v240
	v_add_f32_e32 v241, v120, v121
	v_mfma_f32_16x16x32_bf16 v[212:215], v[76:79], v[100:103], v[212:215]
	v_add_f32_e32 v243, v122, v123
	v_add_f32_e32 v241, v241, v243
	v_add_f32_e32 v243, v124, v125
	v_add_f32_e32 v241, v241, v243
	v_add_f32_e32 v243, v126, v127
	v_add_f32_e32 v241, v241, v243
	v_mfma_f32_16x16x32_bf16 v[216:219], v[72:75], v[108:111], v[216:219]
	v_fma_f32 v156, v156, v245, v241
	v_cvt_pk_bf16_f32 v112, v112, v113
	v_cvt_pk_bf16_f32 v113, v114, v115
	v_cvt_pk_bf16_f32 v114, v116, v117
	v_cvt_pk_bf16_f32 v115, v118, v119
	v_cvt_pk_bf16_f32 v120, v120, v121
	v_mfma_f32_16x16x32_bf16 v[220:223], v[76:79], v[108:111], v[220:223]
	v_cvt_pk_bf16_f32 v121, v122, v123
	v_cvt_pk_bf16_f32 v122, v124, v125
	v_cvt_pk_bf16_f32 v123, v126, v127
	v_cmp_neq_f32_e32 vcc, 1.0, v244
	s_nop 1
	s_cbranch_vccz .Lfoxf_r4
	v_mul_f32_e32 v60, v60, v244
	v_mul_f32_e32 v61, v61, v244
	v_mul_f32_e32 v62, v62, v244
	v_mul_f32_e32 v63, v63, v244
	v_mul_f32_e32 v56, v56, v244
	v_mul_f32_e32 v57, v57, v244
	v_mul_f32_e32 v58, v58, v244
	v_mul_f32_e32 v59, v59, v244
	v_mul_f32_e32 v52, v52, v244
	v_mul_f32_e32 v53, v53, v244
	v_mul_f32_e32 v54, v54, v244
	v_mul_f32_e32 v55, v55, v244
	v_mul_f32_e32 v48, v48, v244
	v_mul_f32_e32 v49, v49, v244
	v_mul_f32_e32 v50, v50, v244
	v_mul_f32_e32 v51, v51, v244

.Lfoxf_r5:
	s_waitcnt lgkmcnt(0)
	v_mfma_f32_16x16x32_bf16 v[60:63], v[80:83], v[112:115], v[60:63]
	v_sub_f32_e32 v208, v208, v232
	v_sub_f32_e32 v209, v209, v233
	v_sub_f32_e32 v210, v210, v234
	v_sub_f32_e32 v211, v211, v235
	v_sub_f32_e32 v212, v212, v236
	v_sub_f32_e32 v213, v213, v237
	v_sub_f32_e32 v214, v214, v238
	v_sub_f32_e32 v215, v215, v239
	v_sub_f32_e32 v216, v216, v232
	v_sub_f32_e32 v217, v217, v233
	v_sub_f32_e32 v218, v218, v234
	v_sub_f32_e32 v219, v219, v235
	v_mfma_f32_16x16x32_bf16 v[44:47], v[80:83], v[120:123], v[44:47]
	v_sub_f32_e32 v220, v220, v236
	v_sub_f32_e32 v221, v221, v237
	v_sub_f32_e32 v222, v222, v238
	v_sub_f32_e32 v223, v223, v239
	v_max3_f32 v240, v208, v209, v210
	v_max3_f32 v240, v240, v211, v212
	v_max3_f32 v240, v240, v213, v214
	v_max_f32_e32 v240, v240, v215
	v_max3_f32 v241, v216, v217, v218
	v_max3_f32 v241, v241, v219, v220
	v_max3_f32 v241, v241, v221, v222
	v_max_f32_e32 v241, v241, v223
	v_mfma_f32_16x16x32_bf16 v[56:59], v[84:87], v[112:115], v[56:59]
	v_add_f32_e32 v240, v240, v168
	v_add_f32_e32 v241, v241, v169
	v_mov_b32_e32 v242, v240
	v_mov_b32_e32 v243, v241
	s_nop 1
	v_permlane16_swap_b32_e32 v240, v242
	v_permlane16_swap_b32_e32 v241, v243
	v_max_f32_e32 v240, v240, v242
	v_max_f32_e32 v241, v241, v243
	v_mov_b32_e32 v242, v240
	v_mov_b32_e32 v243, v241
	s_nop 1
	v_permlane32_swap_b32_e32 v240, v242
	v_permlane32_swap_b32_e32 v241, v243
	v_max3_f32 v240, v167, v240, v242
	v_sub_f32_e32 v244, v167, v240
	v_sub_f32_e32 v246, v240, v168
	v_exp_f32_e32 v244, v244
	v_mov_b32_e32 v167, v240
	v_max3_f32 v241, v166, v241, v243
	v_sub_f32_e32 v245, v166, v241
	v_sub_f32_e32 v247, v241, v169
	v_exp_f32_e32 v245, v245
	v_mov_b32_e32 v166, v241
	v_mfma_f32_16x16x32_bf16 v[36:39], v[84:87], v[120:123], v[36:39]
	v_sub_f32_e32 v208, v208, v246
	v_sub_f32_e32 v209, v209, v246
	v_sub_f32_e32 v210, v210, v246
	v_sub_f32_e32 v211, v211, v246
	v_sub_f32_e32 v212, v212, v246
	v_sub_f32_e32 v213, v213, v246
	v_sub_f32_e32 v214, v214, v246
	v_sub_f32_e32 v215, v215, v246
	v_sub_f32_e32 v216, v216, v247
	v_sub_f32_e32 v217, v217, v247
	v_sub_f32_e32 v218, v218, v247
	v_mfma_f32_16x16x32_bf16 v[52:55], v[88:91], v[112:115], v[52:55]
	v_sub_f32_e32 v219, v219, v247
	v_sub_f32_e32 v220, v220, v247
	v_sub_f32_e32 v221, v221, v247
	v_sub_f32_e32 v222, v222, v247
	v_sub_f32_e32 v223, v223, v247
	v_exp_f32_e32 v208, v208
	v_exp_f32_e32 v209, v209
	v_exp_f32_e32 v210, v210
	v_exp_f32_e32 v211, v211
	v_exp_f32_e32 v212, v212
	v_exp_f32_e32 v213, v213
	v_exp_f32_e32 v214, v214
	v_mfma_f32_16x16x32_bf16 v[32:35], v[88:91], v[120:123], v[32:35]
	v_exp_f32_e32 v215, v215
	v_exp_f32_e32 v216, v216
	v_exp_f32_e32 v217, v217
	v_exp_f32_e32 v218, v218
	v_exp_f32_e32 v219, v219
	v_exp_f32_e32 v220, v220
	v_exp_f32_e32 v221, v221
	v_exp_f32_e32 v222, v222
	v_exp_f32_e32 v223, v223
	v_add_f32_e32 v240, v208, v209
	v_add_f32_e32 v242, v210, v211
	v_add_f32_e32 v240, v240, v242
	v_mfma_f32_16x16x32_bf16 v[48:51], v[92:95], v[112:115], v[48:51]
	v_add_f32_e32 v242, v212, v213
	v_add_f32_e32 v240, v240, v242
	v_add_f32_e32 v242, v214, v215
	v_add_f32_e32 v240, v240, v242
	v_fma_f32 v151, v151, v244, v240
	v_add_f32_e32 v241, v216, v217
	v_add_f32_e32 v243, v218, v219
	v_add_f32_e32 v241, v241, v243
	v_add_f32_e32 v243, v220, v221
	v_add_f32_e32 v241, v241, v243
	v_add_f32_e32 v243, v222, v223
	v_add_f32_e32 v241, v241, v243
	v_mfma_f32_16x16x32_bf16 v[28:31], v[92:95], v[120:123], v[28:31]
	v_fma_f32 v150, v150, v245, v241
	v_cvt_pk_bf16_f32 v208, v208, v209
	v_cvt_pk_bf16_f32 v209, v210, v211
	v_cvt_pk_bf16_f32 v210, v212, v213
	v_cvt_pk_bf16_f32 v211, v214, v215
	v_cvt_pk_bf16_f32 v216, v216, v217
	v_cvt_pk_bf16_f32 v217, v218, v219
	v_cvt_pk_bf16_f32 v218, v220, v221
	v_cvt_pk_bf16_f32 v219, v222, v223
	v_cmp_neq_f32_e32 vcc, 1.0, v244
	s_nop 1
	s_cbranch_vccz .Lfoxf_r6
	v_mul_f32_e32 v40, v40, v244
	v_mul_f32_e32 v41, v41, v244
	v_mul_f32_e32 v42, v42, v244
	v_mul_f32_e32 v43, v43, v244
	v_mul_f32_e32 v24, v24, v244
	v_mul_f32_e32 v25, v25, v244
	v_mul_f32_e32 v26, v26, v244
	v_mul_f32_e32 v27, v27, v244
	v_mul_f32_e32 v20, v20, v244
	v_mul_f32_e32 v21, v21, v244
	v_mul_f32_e32 v22, v22, v244
	v_mul_f32_e32 v23, v23, v244
	v_mul_f32_e32 v16, v16, v244
	v_mul_f32_e32 v17, v17, v244
	v_mul_f32_e32 v18, v18, v244
	v_mul_f32_e32 v19, v19, v244

.Lfoxf_r7:
	v_mfma_f32_16x16x32_bf16 v[40:43], v[80:83], v[208:211], v[40:43]
	v_mfma_f32_16x16x32_bf16 v[12:15], v[80:83], v[216:219], v[12:15]
	v_mfma_f32_16x16x32_bf16 v[24:27], v[84:87], v[208:211], v[24:27]
	v_mfma_f32_16x16x32_bf16 v[8:11], v[84:87], v[216:219], v[8:11]
	v_mfma_f32_16x16x32_bf16 v[20:23], v[88:91], v[208:211], v[20:23]
	v_mfma_f32_16x16x32_bf16 v[0:3], v[88:91], v[216:219], v[0:3]
	v_mfma_f32_16x16x32_bf16 v[16:19], v[92:95], v[208:211], v[16:19]
	v_mfma_f32_16x16x32_bf16 v[4:7], v[92:95], v[216:219], v[4:7]
	s_branch .LBB0_65

.LBB0_251:
	s_add_u32 s8, s82, 0x5950900
	s_addc_u32 s9, s83, 0
	s_add_u32 s10, s82, 0x3950900
	s_addc_u32 s11, s83, 0
	v_lshlrev_b32_e32 v48, 2, v11
	global_load_dword v16, v48, s[2:3]
	global_load_dword v17, v0, s[10:11]
	s_add_u32 s10, s10, 0x4000
	s_addc_u32 s11, s11, 0
	global_load_dword v18, v48, s[2:3] offset:256
	global_load_dword v19, v0, s[10:11]
	s_add_u32 s10, s10, 0x4000
	s_addc_u32 s11, s11, 0
	global_load_dword v20, v48, s[2:3] offset:512
	global_load_dword v21, v0, s[10:11]
	s_add_u32 s10, s10, 0x4000
	s_addc_u32 s11, s11, 0
	global_load_dword v22, v48, s[2:3] offset:768
	global_load_dword v23, v0, s[10:11]
	s_add_u32 s10, s10, 0x4000
	s_addc_u32 s11, s11, 0
	global_load_dword v24, v48, s[2:3] offset:1024
	global_load_dword v25, v0, s[10:11]
	s_add_u32 s10, s10, 0x4000
	s_addc_u32 s11, s11, 0
	global_load_dword v26, v48, s[2:3] offset:1280
	global_load_dword v27, v0, s[10:11]
	s_add_u32 s10, s10, 0x4000
	s_addc_u32 s11, s11, 0
	global_load_dword v28, v48, s[2:3] offset:1536
	global_load_dword v29, v0, s[10:11]
	s_add_u32 s10, s10, 0x4000
	s_addc_u32 s11, s11, 0
	global_load_dword v30, v48, s[2:3] offset:1792
	global_load_dword v31, v0, s[10:11]
	s_add_u32 s10, s10, 0x4000
	s_addc_u32 s11, s11, 0
	global_load_dword v32, v48, s[2:3] offset:2048
	global_load_dword v33, v0, s[10:11]
	s_add_u32 s10, s10, 0x4000
	s_addc_u32 s11, s11, 0
	global_load_dword v34, v48, s[2:3] offset:2304
	global_load_dword v35, v0, s[10:11]
	s_add_u32 s10, s10, 0x4000
	s_addc_u32 s11, s11, 0
	global_load_dword v36, v48, s[2:3] offset:2560
	global_load_dword v37, v0, s[10:11]
	s_add_u32 s10, s10, 0x4000
	s_addc_u32 s11, s11, 0
	global_load_dword v38, v48, s[2:3] offset:2816
	global_load_dword v39, v0, s[10:11]
	s_add_u32 s10, s10, 0x4000
	s_addc_u32 s11, s11, 0
	global_load_dword v40, v48, s[2:3] offset:3072
	global_load_dword v41, v0, s[10:11]
	s_add_u32 s10, s10, 0x4000
	s_addc_u32 s11, s11, 0
	global_load_dword v42, v48, s[2:3] offset:3328
	global_load_dword v43, v0, s[10:11]
	s_add_u32 s10, s10, 0x4000
	s_addc_u32 s11, s11, 0
	global_load_dword v44, v48, s[2:3] offset:3584
	global_load_dword v45, v0, s[10:11]
	s_add_u32 s10, s10, 0x4000
	s_addc_u32 s11, s11, 0
	global_load_dword v46, v48, s[2:3] offset:3840
	global_load_dword v47, v0, s[10:11]
	s_add_u32 s10, s10, 0x4000
	s_addc_u32 s11, s11, 0
	s_waitcnt vmcnt(16)
	v_cvt_pk_bf16_f32 v49, v12, v153
	global_store_short v2, v49, s[8:9]
	s_add_u32 s8, s8, 0x2000
	s_addc_u32 s9, s9, 0
	v_fma_f32 v12, v12, v16, v17
	v_cvt_pk_bf16_f32 v49, v12, v153
	global_store_short v2, v49, s[8:9]
	s_add_u32 s8, s8, 0x2000
	s_addc_u32 s9, s9, 0
	v_fma_f32 v12, v12, v18, v19
	v_cvt_pk_bf16_f32 v49, v12, v153
	global_store_short v2, v49, s[8:9]
	s_add_u32 s8, s8, 0x2000
	s_addc_u32 s9, s9, 0
	v_fma_f32 v12, v12, v20, v21
	v_cvt_pk_bf16_f32 v49, v12, v153
	global_store_short v2, v49, s[8:9]
	s_add_u32 s8, s8, 0x2000
	s_addc_u32 s9, s9, 0
	v_fma_f32 v12, v12, v22, v23
	v_cvt_pk_bf16_f32 v49, v12, v153
	global_store_short v2, v49, s[8:9]
	s_add_u32 s8, s8, 0x2000
	s_addc_u32 s9, s9, 0
	v_fma_f32 v12, v12, v24, v25
	v_cvt_pk_bf16_f32 v49, v12, v153
	global_store_short v2, v49, s[8:9]
	s_add_u32 s8, s8, 0x2000
	s_addc_u32 s9, s9, 0
	v_fma_f32 v12, v12, v26, v27
	v_cvt_pk_bf16_f32 v49, v12, v153
	global_store_short v2, v49, s[8:9]
	s_add_u32 s8, s8, 0x2000
	s_addc_u32 s9, s9, 0
	v_fma_f32 v12, v12, v28, v29
	v_cvt_pk_bf16_f32 v49, v12, v153
	global_store_short v2, v49, s[8:9]
	s_add_u32 s8, s8, 0x2000
	s_addc_u32 s9, s9, 0
	v_fma_f32 v12, v12, v30, v31
	v_add_u32_e32 v48, 0x1000, v48
	global_load_dword v16, v48, s[2:3]
	global_load_dword v17, v0, s[10:11]
	s_add_u32 s10, s10, 0x4000
	s_addc_u32 s11, s11, 0
	global_load_dword v18, v48, s[2:3] offset:256
	global_load_dword v19, v0, s[10:11]
	s_add_u32 s10, s10, 0x4000
	s_addc_u32 s11, s11, 0
	global_load_dword v20, v48, s[2:3] offset:512
	global_load_dword v21, v0, s[10:11]
	s_add_u32 s10, s10, 0x4000
	s_addc_u32 s11, s11, 0
	global_load_dword v22, v48, s[2:3] offset:768
	global_load_dword v23, v0, s[10:11]
	s_add_u32 s10, s10, 0x4000
	s_addc_u32 s11, s11, 0
	global_load_dword v24, v48, s[2:3] offset:1024
	global_load_dword v25, v0, s[10:11]
	s_add_u32 s10, s10, 0x4000
	s_addc_u32 s11, s11, 0
	global_load_dword v26, v48, s[2:3] offset:1280
	global_load_dword v27, v0, s[10:11]
	s_add_u32 s10, s10, 0x4000
	s_addc_u32 s11, s11, 0
	global_load_dword v28, v48, s[2:3] offset:1536
	global_load_dword v29, v0, s[10:11]
	s_add_u32 s10, s10, 0x4000
	s_addc_u32 s11, s11, 0
	global_load_dword v30, v48, s[2:3] offset:1792
	global_load_dword v31, v0, s[10:11]
	s_add_u32 s10, s10, 0x4000
	s_addc_u32 s11, s11, 0
	s_waitcnt vmcnt(24)
	v_cvt_pk_bf16_f32 v49, v12, v153
	global_store_short v2, v49, s[8:9]
	s_add_u32 s8, s8, 0x2000
	s_addc_u32 s9, s9, 0
	v_fma_f32 v12, v12, v32, v33
	v_cvt_pk_bf16_f32 v49, v12, v153
	global_store_short v2, v49, s[8:9]
	s_add_u32 s8, s8, 0x2000
	s_addc_u32 s9, s9, 0
	v_fma_f32 v12, v12, v34, v35
	v_cvt_pk_bf16_f32 v49, v12, v153
	global_store_short v2, v49, s[8:9]
	s_add_u32 s8, s8, 0x2000
	s_addc_u32 s9, s9, 0
	v_fma_f32 v12, v12, v36, v37
	v_cvt_pk_bf16_f32 v49, v12, v153
	global_store_short v2, v49, s[8:9]
	s_add_u32 s8, s8, 0x2000
	s_addc_u32 s9, s9, 0
	v_fma_f32 v12, v12, v38, v39
	v_cvt_pk_bf16_f32 v49, v12, v153
	global_store_short v2, v49, s[8:9]
	s_add_u32 s8, s8, 0x2000
	s_addc_u32 s9, s9, 0
	v_fma_f32 v12, v12, v40, v41
	v_cvt_pk_bf16_f32 v49, v12, v153
	global_store_short v2, v49, s[8:9]
	s_add_u32 s8, s8, 0x2000
	s_addc_u32 s9, s9, 0
	v_fma_f32 v12, v12, v42, v43
	v_cvt_pk_bf16_f32 v49, v12, v153
	global_store_short v2, v49, s[8:9]
	s_add_u32 s8, s8, 0x2000
	s_addc_u32 s9, s9, 0
	v_fma_f32 v12, v12, v44, v45
	v_cvt_pk_bf16_f32 v49, v12, v153
	global_store_short v2, v49, s[8:9]
	s_add_u32 s8, s8, 0x2000
	s_addc_u32 s9, s9, 0
	v_fma_f32 v12, v12, v46, v47
	global_load_dword v32, v48, s[2:3] offset:2048
	global_load_dword v33, v0, s[10:11]
	s_add_u32 s10, s10, 0x4000
	s_addc_u32 s11, s11, 0
	global_load_dword v34, v48, s[2:3] offset:2304
	global_load_dword v35, v0, s[10:11]
	s_add_u32 s10, s10, 0x4000
	s_addc_u32 s11, s11, 0
	global_load_dword v36, v48, s[2:3] offset:2560
	global_load_dword v37, v0, s[10:11]
	s_add_u32 s10, s10, 0x4000
	s_addc_u32 s11, s11, 0
	global_load_dword v38, v48, s[2:3] offset:2816
	global_load_dword v39, v0, s[10:11]
	s_add_u32 s10, s10, 0x4000
	s_addc_u32 s11, s11, 0
	global_load_dword v40, v48, s[2:3] offset:3072
	global_load_dword v41, v0, s[10:11]
	s_add_u32 s10, s10, 0x4000
	s_addc_u32 s11, s11, 0
	global_load_dword v42, v48, s[2:3] offset:3328
	global_load_dword v43, v0, s[10:11]
	s_add_u32 s10, s10, 0x4000
	s_addc_u32 s11, s11, 0
	global_load_dword v44, v48, s[2:3] offset:3584
	global_load_dword v45, v0, s[10:11]
	s_add_u32 s10, s10, 0x4000
	s_addc_u32 s11, s11, 0
	global_load_dword v46, v48, s[2:3] offset:3840
	global_load_dword v47, v0, s[10:11]
	s_add_u32 s10, s10, 0x4000
	s_addc_u32 s11, s11, 0
	s_waitcnt vmcnt(24)
	v_cvt_pk_bf16_f32 v49, v12, v153
	global_store_short v2, v49, s[8:9]
	s_add_u32 s8, s8, 0x2000
	s_addc_u32 s9, s9, 0
	v_fma_f32 v12, v12, v16, v17
	v_cvt_pk_bf16_f32 v49, v12, v153
	global_store_short v2, v49, s[8:9]
	s_add_u32 s8, s8, 0x2000
	s_addc_u32 s9, s9, 0
	v_fma_f32 v12, v12, v18, v19
	v_cvt_pk_bf16_f32 v49, v12, v153
	global_store_short v2, v49, s[8:9]
	s_add_u32 s8, s8, 0x2000
	s_addc_u32 s9, s9, 0
	v_fma_f32 v12, v12, v20, v21
	v_cvt_pk_bf16_f32 v49, v12, v153
	global_store_short v2, v49, s[8:9]
	s_add_u32 s8, s8, 0x2000
	s_addc_u32 s9, s9, 0
	v_fma_f32 v12, v12, v22, v23
	v_cvt_pk_bf16_f32 v49, v12, v153
	global_store_short v2, v49, s[8:9]
	s_add_u32 s8, s8, 0x2000
	s_addc_u32 s9, s9, 0
	v_fma_f32 v12, v12, v24, v25
	v_cvt_pk_bf16_f32 v49, v12, v153
	global_store_short v2, v49, s[8:9]
	s_add_u32 s8, s8, 0x2000
	s_addc_u32 s9, s9, 0
	v_fma_f32 v12, v12, v26, v27
	v_cvt_pk_bf16_f32 v49, v12, v153
	global_store_short v2, v49, s[8:9]
	s_add_u32 s8, s8, 0x2000
	s_addc_u32 s9, s9, 0
	v_fma_f32 v12, v12, v28, v29
	v_cvt_pk_bf16_f32 v49, v12, v153
	global_store_short v2, v49, s[8:9]
	s_add_u32 s8, s8, 0x2000
	s_addc_u32 s9, s9, 0
	v_fma_f32 v12, v12, v30, v31
	v_add_u32_e32 v48, 0x1000, v48
	global_load_dword v16, v48, s[2:3]
	global_load_dword v17, v0, s[10:11]
	s_add_u32 s10, s10, 0x4000
	s_addc_u32 s11, s11, 0
	global_load_dword v18, v48, s[2:3] offset:256
	global_load_dword v19, v0, s[10:11]
	s_add_u32 s10, s10, 0x4000
	s_addc_u32 s11, s11, 0
	global_load_dword v20, v48, s[2:3] offset:512
	global_load_dword v21, v0, s[10:11]
	s_add_u32 s10, s10, 0x4000
	s_addc_u32 s11, s11, 0
	global_load_dword v22, v48, s[2:3] offset:768
	global_load_dword v23, v0, s[10:11]
	s_add_u32 s10, s10, 0x4000
	s_addc_u32 s11, s11, 0
	global_load_dword v24, v48, s[2:3] offset:1024
	global_load_dword v25, v0, s[10:11]
	s_add_u32 s10, s10, 0x4000
	s_addc_u32 s11, s11, 0
	global_load_dword v26, v48, s[2:3] offset:1280
	global_load_dword v27, v0, s[10:11]
	s_add_u32 s10, s10, 0x4000
	s_addc_u32 s11, s11, 0
	global_load_dword v28, v48, s[2:3] offset:1536
	global_load_dword v29, v0, s[10:11]
	s_add_u32 s10, s10, 0x4000
	s_addc_u32 s11, s11, 0
	global_load_dword v30, v48, s[2:3] offset:1792
	global_load_dword v31, v0, s[10:11]
	s_add_u32 s10, s10, 0x4000
	s_addc_u32 s11, s11, 0
	s_waitcnt vmcnt(24)
	v_cvt_pk_bf16_f32 v49, v12, v153
	global_store_short v2, v49, s[8:9]
	s_add_u32 s8, s8, 0x2000
	s_addc_u32 s9, s9, 0
	v_fma_f32 v12, v12, v32, v33
	v_cvt_pk_bf16_f32 v49, v12, v153
	global_store_short v2, v49, s[8:9]
	s_add_u32 s8, s8, 0x2000
	s_addc_u32 s9, s9, 0
	v_fma_f32 v12, v12, v34, v35
	v_cvt_pk_bf16_f32 v49, v12, v153
	global_store_short v2, v49, s[8:9]
	s_add_u32 s8, s8, 0x2000
	s_addc_u32 s9, s9, 0
	v_fma_f32 v12, v12, v36, v37
	v_cvt_pk_bf16_f32 v49, v12, v153
	global_store_short v2, v49, s[8:9]
	s_add_u32 s8, s8, 0x2000
	s_addc_u32 s9, s9, 0
	v_fma_f32 v12, v12, v38, v39
	v_cvt_pk_bf16_f32 v49, v12, v153
	global_store_short v2, v49, s[8:9]
	s_add_u32 s8, s8, 0x2000
	s_addc_u32 s9, s9, 0
	v_fma_f32 v12, v12, v40, v41
	v_cvt_pk_bf16_f32 v49, v12, v153
	global_store_short v2, v49, s[8:9]
	s_add_u32 s8, s8, 0x2000
	s_addc_u32 s9, s9, 0
	v_fma_f32 v12, v12, v42, v43
	v_cvt_pk_bf16_f32 v49, v12, v153
	global_store_short v2, v49, s[8:9]
	s_add_u32 s8, s8, 0x2000
	s_addc_u32 s9, s9, 0
	v_fma_f32 v12, v12, v44, v45
	v_cvt_pk_bf16_f32 v49, v12, v153
	global_store_short v2, v49, s[8:9]
	s_add_u32 s8, s8, 0x2000
	s_addc_u32 s9, s9, 0
	v_fma_f32 v12, v12, v46, v47
	global_load_dword v32, v48, s[2:3] offset:2048
	global_load_dword v33, v0, s[10:11]
	s_add_u32 s10, s10, 0x4000
	s_addc_u32 s11, s11, 0
	global_load_dword v34, v48, s[2:3] offset:2304
	global_load_dword v35, v0, s[10:11]
	s_add_u32 s10, s10, 0x4000
	s_addc_u32 s11, s11, 0
	global_load_dword v36, v48, s[2:3] offset:2560
	global_load_dword v37, v0, s[10:11]
	s_add_u32 s10, s10, 0x4000
	s_addc_u32 s11, s11, 0
	global_load_dword v38, v48, s[2:3] offset:2816
	global_load_dword v39, v0, s[10:11]
	s_add_u32 s10, s10, 0x4000
	s_addc_u32 s11, s11, 0
	global_load_dword v40, v48, s[2:3] offset:3072
	global_load_dword v41, v0, s[10:11]
	s_add_u32 s10, s10, 0x4000
	s_addc_u32 s11, s11, 0
	global_load_dword v42, v48, s[2:3] offset:3328
	global_load_dword v43, v0, s[10:11]
	s_add_u32 s10, s10, 0x4000
	s_addc_u32 s11, s11, 0
	global_load_dword v44, v48, s[2:3] offset:3584
	global_load_dword v45, v0, s[10:11]
	s_add_u32 s10, s10, 0x4000
	s_addc_u32 s11, s11, 0
	global_load_dword v46, v48, s[2:3] offset:3840
	global_load_dword v47, v0, s[10:11]
	s_add_u32 s10, s10, 0x4000
	s_addc_u32 s11, s11, 0
	s_waitcnt vmcnt(24)
	v_cvt_pk_bf16_f32 v49, v12, v153
	global_store_short v2, v49, s[8:9]
	s_add_u32 s8, s8, 0x2000
	s_addc_u32 s9, s9, 0
	v_fma_f32 v12, v12, v16, v17
	v_cvt_pk_bf16_f32 v49, v12, v153
	global_store_short v2, v49, s[8:9]
	s_add_u32 s8, s8, 0x2000
	s_addc_u32 s9, s9, 0
	v_fma_f32 v12, v12, v18, v19
	v_cvt_pk_bf16_f32 v49, v12, v153
	global_store_short v2, v49, s[8:9]
	s_add_u32 s8, s8, 0x2000
	s_addc_u32 s9, s9, 0
	v_fma_f32 v12, v12, v20, v21
	v_cvt_pk_bf16_f32 v49, v12, v153
	global_store_short v2, v49, s[8:9]
	s_add_u32 s8, s8, 0x2000
	s_addc_u32 s9, s9, 0
	v_fma_f32 v12, v12, v22, v23
	v_cvt_pk_bf16_f32 v49, v12, v153
	global_store_short v2, v49, s[8:9]
	s_add_u32 s8, s8, 0x2000
	s_addc_u32 s9, s9, 0
	v_fma_f32 v12, v12, v24, v25
	v_cvt_pk_bf16_f32 v49, v12, v153
	global_store_short v2, v49, s[8:9]
	s_add_u32 s8, s8, 0x2000
	s_addc_u32 s9, s9, 0
	v_fma_f32 v12, v12, v26, v27
	v_cvt_pk_bf16_f32 v49, v12, v153
	global_store_short v2, v49, s[8:9]
	s_add_u32 s8, s8, 0x2000
	s_addc_u32 s9, s9, 0
	v_fma_f32 v12, v12, v28, v29
	v_cvt_pk_bf16_f32 v49, v12, v153
	global_store_short v2, v49, s[8:9]
	s_add_u32 s8, s8, 0x2000
	s_addc_u32 s9, s9, 0
	v_fma_f32 v12, v12, v30, v31
	v_add_u32_e32 v48, 0x1000, v48
	global_load_dword v16, v48, s[2:3]
	global_load_dword v17, v0, s[10:11]
	s_add_u32 s10, s10, 0x4000
	s_addc_u32 s11, s11, 0
	global_load_dword v18, v48, s[2:3] offset:256
	global_load_dword v19, v0, s[10:11]
	s_add_u32 s10, s10, 0x4000
	s_addc_u32 s11, s11, 0
	global_load_dword v20, v48, s[2:3] offset:512
	global_load_dword v21, v0, s[10:11]
	s_add_u32 s10, s10, 0x4000
	s_addc_u32 s11, s11, 0
	global_load_dword v22, v48, s[2:3] offset:768
	global_load_dword v23, v0, s[10:11]
	s_add_u32 s10, s10, 0x4000
	s_addc_u32 s11, s11, 0
	global_load_dword v24, v48, s[2:3] offset:1024
	global_load_dword v25, v0, s[10:11]
	s_add_u32 s10, s10, 0x4000
	s_addc_u32 s11, s11, 0
	global_load_dword v26, v48, s[2:3] offset:1280
	global_load_dword v27, v0, s[10:11]
	s_add_u32 s10, s10, 0x4000
	s_addc_u32 s11, s11, 0
	global_load_dword v28, v48, s[2:3] offset:1536
	global_load_dword v29, v0, s[10:11]
	s_add_u32 s10, s10, 0x4000
	s_addc_u32 s11, s11, 0
	global_load_dword v30, v48, s[2:3] offset:1792
	global_load_dword v31, v0, s[10:11]
	s_add_u32 s10, s10, 0x4000
	s_addc_u32 s11, s11, 0
	s_waitcnt vmcnt(24)
	v_cvt_pk_bf16_f32 v49, v12, v153
	global_store_short v2, v49, s[8:9]
	s_add_u32 s8, s8, 0x2000
	s_addc_u32 s9, s9, 0
	v_fma_f32 v12, v12, v32, v33
	v_cvt_pk_bf16_f32 v49, v12, v153
	global_store_short v2, v49, s[8:9]
	s_add_u32 s8, s8, 0x2000
	s_addc_u32 s9, s9, 0
	v_fma_f32 v12, v12, v34, v35
	v_cvt_pk_bf16_f32 v49, v12, v153
	global_store_short v2, v49, s[8:9]
	s_add_u32 s8, s8, 0x2000
	s_addc_u32 s9, s9, 0
	v_fma_f32 v12, v12, v36, v37
	v_cvt_pk_bf16_f32 v49, v12, v153
	global_store_short v2, v49, s[8:9]
	s_add_u32 s8, s8, 0x2000
	s_addc_u32 s9, s9, 0
	v_fma_f32 v12, v12, v38, v39
	v_cvt_pk_bf16_f32 v49, v12, v153
	global_store_short v2, v49, s[8:9]
	s_add_u32 s8, s8, 0x2000
	s_addc_u32 s9, s9, 0
	v_fma_f32 v12, v12, v40, v41
	v_cvt_pk_bf16_f32 v49, v12, v153
	global_store_short v2, v49, s[8:9]
	s_add_u32 s8, s8, 0x2000
	s_addc_u32 s9, s9, 0
	v_fma_f32 v12, v12, v42, v43
	v_cvt_pk_bf16_f32 v49, v12, v153
	global_store_short v2, v49, s[8:9]
	s_add_u32 s8, s8, 0x2000
	s_addc_u32 s9, s9, 0
	v_fma_f32 v12, v12, v44, v45
	v_cvt_pk_bf16_f32 v49, v12, v153
	global_store_short v2, v49, s[8:9]
	s_add_u32 s8, s8, 0x2000
	s_addc_u32 s9, s9, 0
	v_fma_f32 v12, v12, v46, v47
	global_load_dword v32, v48, s[2:3] offset:2048
	global_load_dword v33, v0, s[10:11]
	s_add_u32 s10, s10, 0x4000
	s_addc_u32 s11, s11, 0
	global_load_dword v34, v48, s[2:3] offset:2304
	global_load_dword v35, v0, s[10:11]
	s_add_u32 s10, s10, 0x4000
	s_addc_u32 s11, s11, 0
	global_load_dword v36, v48, s[2:3] offset:2560
	global_load_dword v37, v0, s[10:11]
	s_add_u32 s10, s10, 0x4000
	s_addc_u32 s11, s11, 0
	global_load_dword v38, v48, s[2:3] offset:2816
	global_load_dword v39, v0, s[10:11]
	s_add_u32 s10, s10, 0x4000
	s_addc_u32 s11, s11, 0
	global_load_dword v40, v48, s[2:3] offset:3072
	global_load_dword v41, v0, s[10:11]
	s_add_u32 s10, s10, 0x4000
	s_addc_u32 s11, s11, 0
	global_load_dword v42, v48, s[2:3] offset:3328
	global_load_dword v43, v0, s[10:11]
	s_add_u32 s10, s10, 0x4000
	s_addc_u32 s11, s11, 0
	global_load_dword v44, v48, s[2:3] offset:3584
	global_load_dword v45, v0, s[10:11]
	s_add_u32 s10, s10, 0x4000
	s_addc_u32 s11, s11, 0
	global_load_dword v46, v48, s[2:3] offset:3840
	global_load_dword v47, v0, s[10:11]
	s_add_u32 s10, s10, 0x4000
	s_addc_u32 s11, s11, 0
	s_waitcnt vmcnt(24)
	v_cvt_pk_bf16_f32 v49, v12, v153
	global_store_short v2, v49, s[8:9]
	s_add_u32 s8, s8, 0x2000
	s_addc_u32 s9, s9, 0
	v_fma_f32 v12, v12, v16, v17
	v_cvt_pk_bf16_f32 v49, v12, v153
	global_store_short v2, v49, s[8:9]
	s_add_u32 s8, s8, 0x2000
	s_addc_u32 s9, s9, 0
	v_fma_f32 v12, v12, v18, v19
	v_cvt_pk_bf16_f32 v49, v12, v153
	global_store_short v2, v49, s[8:9]
	s_add_u32 s8, s8, 0x2000
	s_addc_u32 s9, s9, 0
	v_fma_f32 v12, v12, v20, v21
	v_cvt_pk_bf16_f32 v49, v12, v153
	global_store_short v2, v49, s[8:9]
	s_add_u32 s8, s8, 0x2000
	s_addc_u32 s9, s9, 0
	v_fma_f32 v12, v12, v22, v23
	v_cvt_pk_bf16_f32 v49, v12, v153
	global_store_short v2, v49, s[8:9]
	s_add_u32 s8, s8, 0x2000
	s_addc_u32 s9, s9, 0
	v_fma_f32 v12, v12, v24, v25
	v_cvt_pk_bf16_f32 v49, v12, v153
	global_store_short v2, v49, s[8:9]
	s_add_u32 s8, s8, 0x2000
	s_addc_u32 s9, s9, 0
	v_fma_f32 v12, v12, v26, v27
	v_cvt_pk_bf16_f32 v49, v12, v153
	global_store_short v2, v49, s[8:9]
	s_add_u32 s8, s8, 0x2000
	s_addc_u32 s9, s9, 0
	v_fma_f32 v12, v12, v28, v29
	v_cvt_pk_bf16_f32 v49, v12, v153
	global_store_short v2, v49, s[8:9]
	s_add_u32 s8, s8, 0x2000
	s_addc_u32 s9, s9, 0
	v_fma_f32 v12, v12, v30, v31
	s_waitcnt vmcnt(8)
	v_cvt_pk_bf16_f32 v49, v12, v153
	global_store_short v2, v49, s[8:9]
	s_add_u32 s8, s8, 0x2000
	s_addc_u32 s9, s9, 0
	v_fma_f32 v12, v12, v32, v33
	v_cvt_pk_bf16_f32 v49, v12, v153
	global_store_short v2, v49, s[8:9]
	s_add_u32 s8, s8, 0x2000
	s_addc_u32 s9, s9, 0
	v_fma_f32 v12, v12, v34, v35
	v_cvt_pk_bf16_f32 v49, v12, v153
	global_store_short v2, v49, s[8:9]
	s_add_u32 s8, s8, 0x2000
	s_addc_u32 s9, s9, 0
	v_fma_f32 v12, v12, v36, v37
	v_cvt_pk_bf16_f32 v49, v12, v153
	global_store_short v2, v49, s[8:9]
	s_add_u32 s8, s8, 0x2000
	s_addc_u32 s9, s9, 0
	v_fma_f32 v12, v12, v38, v39
	v_cvt_pk_bf16_f32 v49, v12, v153
	global_store_short v2, v49, s[8:9]
	s_add_u32 s8, s8, 0x2000
	s_addc_u32 s9, s9, 0
	v_fma_f32 v12, v12, v40, v41
	v_cvt_pk_bf16_f32 v49, v12, v153
	global_store_short v2, v49, s[8:9]
	s_add_u32 s8, s8, 0x2000
	s_addc_u32 s9, s9, 0
	v_fma_f32 v12, v12, v42, v43
	v_cvt_pk_bf16_f32 v49, v12, v153
	global_store_short v2, v49, s[8:9]
	s_add_u32 s8, s8, 0x2000
	s_addc_u32 s9, s9, 0
	v_fma_f32 v12, v12, v44, v45
	v_cvt_pk_bf16_f32 v49, v12, v153
	global_store_short v2, v49, s[8:9]
	s_add_u32 s8, s8, 0x2000
	s_addc_u32 s9, s9, 0
	v_fma_f32 v12, v12, v46, v47
	s_load_dword s8, s[88:89], 0x0
	s_waitcnt lgkmcnt(0)
	v_lshl_add_u32 v10, s8, 8, v10
	s_mov_b32 s8, 0x1ffff
	v_cmp_lt_i32_e32 vcc, s8, v10
	s_or_b64 s[6:7], vcc, s[6:7]
	s_andn2_b64 exec, exec, s[6:7]
	s_cbranch_execnz .LBB0_250
